# snake MFMA order: accumulate chains back to back, k order alternating so every chain boundary shares a source operand (+ VALU-free load segments)
# baseline (speedup 1.0000x reference)
; #define PG8_STAGE(bufoff, gbase, voff) do { const char* gb_ = (const char*)(gbase); asm volatile("" : "+s"(gb_)); _Pragma("unroll") for (int _i = 0; _i < 2; ++_i) { unsigned vo_ = (voff)[_i]; asm volatile("" : "+v"(vo_));        \
;         __builtin_amdgcn_global_load_lds((const unsigned*)(gb_ + vo_), (PG8_LAS unsigned*)(lds + (bufoff) + ldsw + _i * 8192), 16, 0, 0); } } while (0)
; #define PG8_LDA(dst, b, h) do { _Pragma("unroll") for (int m = 0; m < 4; ++m) _Pragma("unroll") for (int k = 0; k < 2; ++k) dst[m][k] = *(const PG8_LAS bf16x8*)(lds + PG8_SA(b, h) + aoff + m * 2048 + k * 1024); } while (0)
; #define PG8_LDB(dst, b, h) do { _Pragma("unroll") for (int n = 0; n < 2; ++n) _Pragma("unroll") for (int k = 0; k < 2; ++k) dst[n][k] = *(const PG8_LAS bf16x8*)(lds + PG8_SB(b, h) + boff + n * 2048 + k * 1024); } while (0)
; #define PG8_MMA(ai, bj, At, Bt) do { __builtin_amdgcn_s_setprio(1); _Pragma("unroll") for (int m = 0; m < 4; ++m) _Pragma("unroll") for (int n = 0; n < 2; ++n) _Pragma("unroll") for (int k = 0; k < 2; ++k) \
;         acc[ai][bj][m][n] = __builtin_amdgcn_mfma_f32_16x16x32_bf16(Bt[n][k], At[m][k], acc[ai][bj][m][n], 0, 0, 0); __builtin_amdgcn_s_setprio(0); } while (0)
; #define PG8_WAIT_V(n) asm volatile("s_waitcnt vmcnt(" #n ")" ::: "memory")
; template <class Epi, class Sched, bool ALIGN_EPI = false, bool SP2 = false>
; __device__ __forceinline__ void gemm_phase(PG8_LAS unsigned char* lds, const Gemm g, const Sched& S, const Epi& E) {
;     ...
;             const bool last = (t == nt - 2);
;             const char* a1 = cA + (size_t)(t + 1) * kstep;
;             const char* a2 = last ? nA : cA + (size_t)(t + 2) * kstep; const char* b2 = last ? nB : cB + (size_t)(t + 2) * kstep;
;             const char* a3 = a2 + kstep; const char* b3 = b2 + kstep;
;             if (last && has_next) S.a_ready(nxt);
;             if constexpr (SP2) {
;             PG8_LDB(B0, 0, 0); PG8_LDB(B1, 0, 1); PG8_SCHED; PG8_LDA(At, 0, 0); PG8_STAGE(PG8_SA(1, 1), a1 + hstep, voffA);
;             PG8_WAIT_V(8); PG8_WAIT_L(0); PG8_BAR; PG8_MMA(0, 0, At, B0); PG8_MMA(0, 1, At, B1); PG8_BAR; PG8_SCHED;
;             PG8_LDA(At, 0, 1); PG8_STAGE(PG8_SB(0, 0), b2, voffB); PG8_STAGE(PG8_SB(0, 1), b2 + hstep, voffB); PG8_STAGE(PG8_SA(0, 0), a2, voffA);
;             PG8_WAIT_V(8); PG8_WAIT_L(0); PG8_BAR; PG8_MMA(1, 0, At, B0); PG8_MMA(1, 1, At, B1); PG8_BAR; PG8_SCHED;
.LBB0_232:
	s_add_u32 s2, s0, 0x100
	s_addc_u32 s3, s1, 0
	s_cmp_eq_u32 s30, 28
	s_cselect_b32 s10, s25, s2
	s_cselect_b32 s11, s24, s3
	s_cselect_b32 s8, s27, s28
	s_cselect_b32 s9, s26, s29
	s_add_u32 s6, s10, 0x80
	s_addc_u32 s7, s11, 0
	s_add_i32 s31, 0, 0x10000
	s_add_i32 s33, 0, 0x14000
	ds_read_b128 v[66:69], v244
	ds_read_b128 v[70:73], v244 offset:1024
	ds_read_b128 v[74:77], v244 offset:2048
	ds_read_b128 v[78:81], v244 offset:3072
	ds_read_b128 v[146:149], v244 offset:16384
	ds_read_b128 v[150:153], v244 offset:17408
	ds_read_b128 v[154:157], v244 offset:18432
	ds_read_b128 v[158:161], v244 offset:19456
	s_add_u32 s0, s0, 0x80080
	s_addc_u32 s1, s1, 0
	ds_read_b128 v[178:181], v223
	ds_read_b128 v[182:185], v223 offset:1024
	ds_read_b128 v[192:195], v223 offset:2048
	ds_read_b128 v[196:199], v223 offset:3072
	ds_read_b128 v[200:203], v223 offset:4096
	ds_read_b128 v[204:207], v223 offset:5120
	ds_read_b128 v[208:211], v223 offset:6144
	ds_read_b128 v[212:215], v223 offset:7168
	s_add_i32 m0, s13, 0xc000
	s_nop 0
	global_load_lds_dwordx4 v1, s[0:1]
	s_add_i32 m0, s13, 0xe000
	s_nop 0
	global_load_lds_dwordx4 v191, s[0:1]
	s_waitcnt vmcnt(8)
	s_waitcnt lgkmcnt(0)
	s_barrier
	s_setprio 1
	s_waitcnt lgkmcnt(0)
	v_mfma_f32_16x16x32_bf16 v[142:145], v[66:69], v[178:181], v[142:145]
	v_mfma_f32_16x16x32_bf16 v[142:145], v[70:73], v[182:185], v[142:145]
	v_mfma_f32_16x16x32_bf16 v[138:141], v[78:81], v[182:185], v[138:141]
	v_mfma_f32_16x16x32_bf16 v[138:141], v[74:77], v[178:181], v[138:141]
	v_mfma_f32_16x16x32_bf16 v[130:133], v[74:77], v[192:195], v[130:133]
	v_mfma_f32_16x16x32_bf16 v[130:133], v[78:81], v[196:199], v[130:133]
	v_mfma_f32_16x16x32_bf16 v[134:137], v[70:73], v[196:199], v[134:137]
	v_mfma_f32_16x16x32_bf16 v[134:137], v[66:69], v[192:195], v[134:137]
	v_mfma_f32_16x16x32_bf16 v[126:129], v[66:69], v[200:203], v[126:129]
	v_mfma_f32_16x16x32_bf16 v[126:129], v[70:73], v[204:207], v[126:129]
	v_mfma_f32_16x16x32_bf16 v[122:125], v[78:81], v[204:207], v[122:125]
	v_mfma_f32_16x16x32_bf16 v[122:125], v[74:77], v[200:203], v[122:125]
	v_mfma_f32_16x16x32_bf16 v[114:117], v[74:77], v[208:211], v[114:117]
	v_mfma_f32_16x16x32_bf16 v[114:117], v[78:81], v[212:215], v[114:117]
	v_mfma_f32_16x16x32_bf16 v[118:121], v[70:73], v[212:215], v[118:121]
	v_mfma_f32_16x16x32_bf16 v[118:121], v[66:69], v[208:211], v[118:121]
	s_setprio 0
	s_setprio 1
	v_mfma_f32_16x16x32_bf16 v[62:65], v[146:149], v[178:181], v[62:65]
	v_mfma_f32_16x16x32_bf16 v[62:65], v[150:153], v[182:185], v[62:65]
	v_mfma_f32_16x16x32_bf16 v[58:61], v[158:161], v[182:185], v[58:61]
	v_mfma_f32_16x16x32_bf16 v[58:61], v[154:157], v[178:181], v[58:61]
	v_mfma_f32_16x16x32_bf16 v[50:53], v[154:157], v[192:195], v[50:53]
	v_mfma_f32_16x16x32_bf16 v[50:53], v[158:161], v[196:199], v[50:53]
	v_mfma_f32_16x16x32_bf16 v[54:57], v[150:153], v[196:199], v[54:57]
	v_mfma_f32_16x16x32_bf16 v[54:57], v[146:149], v[192:195], v[54:57]
	v_mfma_f32_16x16x32_bf16 v[46:49], v[146:149], v[200:203], v[46:49]
	v_mfma_f32_16x16x32_bf16 v[46:49], v[150:153], v[204:207], v[46:49]
	v_mfma_f32_16x16x32_bf16 v[42:45], v[158:161], v[204:207], v[42:45]
	v_mfma_f32_16x16x32_bf16 v[42:45], v[154:157], v[200:203], v[42:45]
	v_mfma_f32_16x16x32_bf16 v[34:37], v[154:157], v[208:211], v[34:37]
	v_mfma_f32_16x16x32_bf16 v[34:37], v[158:161], v[212:215], v[34:37]
	v_mfma_f32_16x16x32_bf16 v[38:41], v[150:153], v[212:215], v[38:41]
	v_mfma_f32_16x16x32_bf16 v[38:41], v[146:149], v[208:211], v[38:41]
	s_setprio 0
	s_barrier
	s_mov_b64 s[0:1], s[8:9]
	s_add_i32 s31, s31, s12
	ds_read_b128 v[178:181], v223 offset:16384
	ds_read_b128 v[182:185], v223 offset:17408
	ds_read_b128 v[192:195], v223 offset:18432
	ds_read_b128 v[196:199], v223 offset:19456
	ds_read_b128 v[200:203], v223 offset:20480
	ds_read_b128 v[204:207], v223 offset:21504
	ds_read_b128 v[208:211], v223 offset:22528
	ds_read_b128 v[212:215], v223 offset:23552
	s_mov_b32 m0, s31
	s_nop 0
	global_load_lds_dwordx4 v189, s[0:1]
	s_add_i32 m0, s31, 0x2000
	s_nop 0
	global_load_lds_dwordx4 v219, s[0:1]
	s_add_u32 s0, s8, 0x80000
	s_addc_u32 s1, s9, 0
	s_add_i32 s31, s33, s12
	s_mov_b32 m0, s31
	s_nop 0
	global_load_lds_dwordx4 v189, s[0:1]
	s_add_i32 m0, s31, 0x2000
	s_nop 0
	global_load_lds_dwordx4 v219, s[0:1]
	s_mov_b64 s[0:1], s[10:11]
	s_mov_b32 m0, s13
	s_nop 0
	global_load_lds_dwordx4 v1, s[0:1]
	s_mov_b32 m0, s14
	s_nop 0
	global_load_lds_dwordx4 v191, s[0:1]
	s_waitcnt vmcnt(8)
	s_waitcnt lgkmcnt(0)
	s_barrier
	s_setprio 1
	s_waitcnt lgkmcnt(0)
	v_mfma_f32_16x16x32_bf16 v[110:113], v[66:69], v[178:181], v[110:113]
	v_mfma_f32_16x16x32_bf16 v[110:113], v[70:73], v[182:185], v[110:113]
	v_mfma_f32_16x16x32_bf16 v[106:109], v[74:77], v[178:181], v[106:109]
	v_mfma_f32_16x16x32_bf16 v[106:109], v[78:81], v[182:185], v[106:109]
	v_mfma_f32_16x16x32_bf16 v[102:105], v[66:69], v[192:195], v[102:105]
	v_mfma_f32_16x16x32_bf16 v[102:105], v[70:73], v[196:199], v[102:105]
	v_mfma_f32_16x16x32_bf16 v[98:101], v[74:77], v[192:195], v[98:101]
	v_mfma_f32_16x16x32_bf16 v[98:101], v[78:81], v[196:199], v[98:101]
	v_mfma_f32_16x16x32_bf16 v[94:97], v[66:69], v[200:203], v[94:97]
	v_mfma_f32_16x16x32_bf16 v[94:97], v[70:73], v[204:207], v[94:97]
	v_mfma_f32_16x16x32_bf16 v[90:93], v[74:77], v[200:203], v[90:93]
	v_mfma_f32_16x16x32_bf16 v[90:93], v[78:81], v[204:207], v[90:93]
	v_mfma_f32_16x16x32_bf16 v[66:69], v[66:69], v[208:211], v[86:89]
	v_mfma_f32_16x16x32_bf16 v[66:69], v[70:73], v[212:215], v[66:69]
	v_mfma_f32_16x16x32_bf16 v[70:73], v[74:77], v[208:211], v[82:85]
	v_mfma_f32_16x16x32_bf16 v[70:73], v[78:81], v[212:215], v[70:73]
	s_setprio 0
	s_setprio 1
	v_mfma_f32_16x16x32_bf16 v[30:33], v[146:149], v[178:181], v[30:33]
	v_mfma_f32_16x16x32_bf16 v[30:33], v[150:153], v[182:185], v[30:33]
	v_mfma_f32_16x16x32_bf16 v[26:29], v[158:161], v[182:185], v[26:29]
	v_mfma_f32_16x16x32_bf16 v[26:29], v[154:157], v[178:181], v[26:29]
	v_mfma_f32_16x16x32_bf16 v[18:21], v[154:157], v[192:195], v[18:21]
	v_mfma_f32_16x16x32_bf16 v[18:21], v[158:161], v[196:199], v[18:21]
	v_mfma_f32_16x16x32_bf16 v[22:25], v[150:153], v[196:199], v[22:25]
	v_mfma_f32_16x16x32_bf16 v[22:25], v[146:149], v[192:195], v[22:25]
	v_mfma_f32_16x16x32_bf16 v[14:17], v[146:149], v[200:203], v[14:17]
	v_mfma_f32_16x16x32_bf16 v[14:17], v[150:153], v[204:207], v[14:17]
	v_mfma_f32_16x16x32_bf16 v[10:13], v[158:161], v[204:207], v[10:13]
	v_mfma_f32_16x16x32_bf16 v[10:13], v[154:157], v[200:203], v[10:13]
	v_mfma_f32_16x16x32_bf16 v[2:5], v[154:157], v[208:211], v[2:5]
	v_mfma_f32_16x16x32_bf16 v[2:5], v[158:161], v[212:215], v[2:5]
	v_mfma_f32_16x16x32_bf16 v[6:9], v[150:153], v[212:215], v[6:9]
	v_mfma_f32_16x16x32_bf16 v[6:9], v[146:149], v[208:211], v[6:9]
	s_setprio 0
	s_barrier
; #define PG8_STAGE(bufoff, gbase, voff) do { const char* gb_ = (const char*)(gbase); asm volatile("" : "+s"(gb_)); _Pragma("unroll") for (int _i = 0; _i < 2; ++_i) { unsigned vo_ = (voff)[_i]; asm volatile("" : "+v"(vo_));        \
;         __builtin_amdgcn_global_load_lds((const unsigned*)(gb_ + vo_), (PG8_LAS unsigned*)(lds + (bufoff) + ldsw + _i * 8192), 16, 0, 0); } } while (0)
; #define PG8_LDA(dst, b, h) do { _Pragma("unroll") for (int m = 0; m < 4; ++m) _Pragma("unroll") for (int k = 0; k < 2; ++k) dst[m][k] = *(const PG8_LAS bf16x8*)(lds + PG8_SA(b, h) + aoff + m * 2048 + k * 1024); } while (0)
; #define PG8_LDB(dst, b, h) do { _Pragma("unroll") for (int n = 0; n < 2; ++n) _Pragma("unroll") for (int k = 0; k < 2; ++k) dst[n][k] = *(const PG8_LAS bf16x8*)(lds + PG8_SB(b, h) + boff + n * 2048 + k * 1024); } while (0)
; #define PG8_MMA(ai, bj, At, Bt) do { __builtin_amdgcn_s_setprio(1); _Pragma("unroll") for (int m = 0; m < 4; ++m) _Pragma("unroll") for (int n = 0; n < 2; ++n) _Pragma("unroll") for (int k = 0; k < 2; ++k) \
;         acc[ai][bj][m][n] = __builtin_amdgcn_mfma_f32_16x16x32_bf16(Bt[n][k], At[m][k], acc[ai][bj][m][n], 0, 0, 0); __builtin_amdgcn_s_setprio(0); } while (0)
; #define PG8_WAIT_V(n) asm volatile("s_waitcnt vmcnt(" #n ")" ::: "memory")
; #define PG8_WAIT_L(n) asm volatile("s_waitcnt lgkmcnt(" #n ")" ::: "memory")
; #define PG8_BAR __builtin_amdgcn_s_barrier()
; #define PG8_SCHED __builtin_amdgcn_sched_barrier(0)
; template <class Epi, class Sched, bool ALIGN_EPI = false, bool SP2 = false>
; __device__ __forceinline__ void gemm_phase(PG8_LAS unsigned char* lds, const Gemm g, const Sched& S, const Epi& E) {
;     ...
;             PG8_LDB(B0, 1, 0); PG8_LDB(B1, 1, 1); PG8_SCHED; PG8_LDA(At, 1, 0); PG8_STAGE(PG8_SA(0, 1), a2 + hstep, voffA);
;             PG8_WAIT_V(8); PG8_WAIT_L(0); PG8_BAR; PG8_MMA(0, 0, At, B0); PG8_MMA(0, 1, At, B1); PG8_BAR; PG8_SCHED;
;             PG8_LDA(At, 1, 1); PG8_STAGE(PG8_SB(1, 0), b3, voffB); PG8_STAGE(PG8_SB(1, 1), b3 + hstep, voffB); PG8_STAGE(PG8_SA(1, 0), a3, voffA);
;             PG8_WAIT_V(8); PG8_WAIT_L(0); PG8_BAR; PG8_MMA(1, 0, At, B0); PG8_MMA(1, 1, At, B1); PG8_BAR; PG8_SCHED;
	s_add_i32 s31, 0, 0x18000
	s_add_i32 s33, 0, 0x1c000
	ds_read_b128 v[74:77], v244 offset:32768
	ds_read_b128 v[78:81], v244 offset:33792
	ds_read_b128 v[82:85], v244 offset:34816
	ds_read_b128 v[146:149], v244 offset:35840
	ds_read_b128 v[150:153], v244 offset:49152
	ds_read_b128 v[154:157], v244 offset:50176
	ds_read_b128 v[158:161], v244 offset:51200
	ds_read_b128 v[178:181], v244 offset:52224
	s_add_u32 s0, s10, 0x80000
	s_addc_u32 s1, s11, 0
	s_mov_b32 m0, s15
	ds_read_b128 v[86:89], v223 offset:32768
	ds_read_b128 v[182:185], v223 offset:33792
	ds_read_b128 v[192:195], v223 offset:34816
	ds_read_b128 v[196:199], v223 offset:35840
	ds_read_b128 v[200:203], v223 offset:36864
	ds_read_b128 v[204:207], v223 offset:37888
	ds_read_b128 v[208:211], v223 offset:38912
	ds_read_b128 v[212:215], v223 offset:39936
	s_nop 0
	global_load_lds_dwordx4 v1, s[0:1]
	s_mov_b32 m0, s16
	s_nop 0
	global_load_lds_dwordx4 v191, s[0:1]
	s_waitcnt vmcnt(8)
	s_waitcnt lgkmcnt(0)
	s_barrier
	s_setprio 1
	s_waitcnt lgkmcnt(0)
	v_mfma_f32_16x16x32_bf16 v[142:145], v[74:77], v[86:89], v[142:145]
	v_mfma_f32_16x16x32_bf16 v[142:145], v[78:81], v[182:185], v[142:145]
	v_mfma_f32_16x16x32_bf16 v[138:141], v[146:149], v[182:185], v[138:141]
	v_mfma_f32_16x16x32_bf16 v[138:141], v[82:85], v[86:89], v[138:141]
	v_mfma_f32_16x16x32_bf16 v[130:133], v[82:85], v[192:195], v[130:133]
	v_mfma_f32_16x16x32_bf16 v[130:133], v[146:149], v[196:199], v[130:133]
	v_mfma_f32_16x16x32_bf16 v[134:137], v[78:81], v[196:199], v[134:137]
	v_mfma_f32_16x16x32_bf16 v[134:137], v[74:77], v[192:195], v[134:137]
	v_mfma_f32_16x16x32_bf16 v[126:129], v[74:77], v[200:203], v[126:129]
	v_mfma_f32_16x16x32_bf16 v[126:129], v[78:81], v[204:207], v[126:129]
	v_mfma_f32_16x16x32_bf16 v[122:125], v[146:149], v[204:207], v[122:125]
	v_mfma_f32_16x16x32_bf16 v[122:125], v[82:85], v[200:203], v[122:125]
	v_mfma_f32_16x16x32_bf16 v[114:117], v[82:85], v[208:211], v[114:117]
	v_mfma_f32_16x16x32_bf16 v[114:117], v[146:149], v[212:215], v[114:117]
	v_mfma_f32_16x16x32_bf16 v[118:121], v[78:81], v[212:215], v[118:121]
	v_mfma_f32_16x16x32_bf16 v[118:121], v[74:77], v[208:211], v[118:121]
	s_setprio 0
	s_setprio 1
	v_mfma_f32_16x16x32_bf16 v[62:65], v[150:153], v[86:89], v[62:65]
	v_mfma_f32_16x16x32_bf16 v[62:65], v[154:157], v[182:185], v[62:65]
	v_mfma_f32_16x16x32_bf16 v[58:61], v[178:181], v[182:185], v[58:61]
	v_mfma_f32_16x16x32_bf16 v[58:61], v[158:161], v[86:89], v[58:61]
	v_mfma_f32_16x16x32_bf16 v[50:53], v[158:161], v[192:195], v[50:53]
	v_mfma_f32_16x16x32_bf16 v[50:53], v[178:181], v[196:199], v[50:53]
	v_mfma_f32_16x16x32_bf16 v[54:57], v[154:157], v[196:199], v[54:57]
	v_mfma_f32_16x16x32_bf16 v[54:57], v[150:153], v[192:195], v[54:57]
	v_mfma_f32_16x16x32_bf16 v[46:49], v[150:153], v[200:203], v[46:49]
	v_mfma_f32_16x16x32_bf16 v[46:49], v[154:157], v[204:207], v[46:49]
	v_mfma_f32_16x16x32_bf16 v[42:45], v[178:181], v[204:207], v[42:45]
	v_mfma_f32_16x16x32_bf16 v[42:45], v[158:161], v[200:203], v[42:45]
	v_mfma_f32_16x16x32_bf16 v[34:37], v[158:161], v[208:211], v[34:37]
	v_mfma_f32_16x16x32_bf16 v[34:37], v[178:181], v[212:215], v[34:37]
	v_mfma_f32_16x16x32_bf16 v[38:41], v[154:157], v[212:215], v[38:41]
	v_mfma_f32_16x16x32_bf16 v[38:41], v[150:153], v[208:211], v[38:41]
	s_setprio 0
	s_barrier
	s_add_u32 s0, s8, 0x80
	s_addc_u32 s1, s9, 0
	s_add_i32 s10, s31, s12
	ds_read_b128 v[182:185], v223 offset:49152
	ds_read_b128 v[192:195], v223 offset:50176
	ds_read_b128 v[196:199], v223 offset:51200
	ds_read_b128 v[200:203], v223 offset:52224
	ds_read_b128 v[204:207], v223 offset:53248
	ds_read_b128 v[208:211], v223 offset:54272
	ds_read_b128 v[212:215], v223 offset:55296
	ds_read_b128 v[224:227], v223 offset:56320
	s_mov_b32 m0, s10
	s_nop 0
	global_load_lds_dwordx4 v189, s[0:1]
	s_add_i32 m0, s10, 0x2000
	s_nop 0
	global_load_lds_dwordx4 v219, s[0:1]
	s_add_u32 s0, s8, 0x80080
	s_addc_u32 s1, s9, 0
	s_add_i32 s8, s33, s12
	s_mov_b32 m0, s8
	s_nop 0
	global_load_lds_dwordx4 v189, s[0:1]
	s_add_i32 m0, s8, 0x2000
	s_nop 0
	global_load_lds_dwordx4 v219, s[0:1]
	s_mov_b32 m0, s19
	s_nop 0
	global_load_lds_dwordx4 v1, s[6:7]
	s_mov_b32 m0, s20
	s_nop 0
	global_load_lds_dwordx4 v191, s[6:7]
	s_waitcnt vmcnt(8)
	s_waitcnt lgkmcnt(0)
	s_barrier
	s_setprio 1
	s_waitcnt lgkmcnt(0)
	v_mfma_f32_16x16x32_bf16 v[86:89], v[74:77], v[182:185], v[110:113]
	v_mfma_f32_16x16x32_bf16 v[110:113], v[78:81], v[192:195], v[86:89]
	v_mfma_f32_16x16x32_bf16 v[86:89], v[82:85], v[182:185], v[106:109]
	v_mfma_f32_16x16x32_bf16 v[106:109], v[146:149], v[192:195], v[86:89]
	v_mfma_f32_16x16x32_bf16 v[86:89], v[74:77], v[196:199], v[102:105]
	v_mfma_f32_16x16x32_bf16 v[102:105], v[78:81], v[200:203], v[86:89]
	v_mfma_f32_16x16x32_bf16 v[86:89], v[82:85], v[196:199], v[98:101]
	v_mfma_f32_16x16x32_bf16 v[98:101], v[146:149], v[200:203], v[86:89]
	v_mfma_f32_16x16x32_bf16 v[86:89], v[74:77], v[204:207], v[94:97]
	v_mfma_f32_16x16x32_bf16 v[94:97], v[78:81], v[208:211], v[86:89]
	v_mfma_f32_16x16x32_bf16 v[86:89], v[82:85], v[204:207], v[90:93]
	v_mfma_f32_16x16x32_bf16 v[90:93], v[146:149], v[208:211], v[86:89]
	v_mfma_f32_16x16x32_bf16 v[66:69], v[74:77], v[212:215], v[66:69]
	v_mfma_f32_16x16x32_bf16 v[86:89], v[78:81], v[224:227], v[66:69]
	v_mfma_f32_16x16x32_bf16 v[66:69], v[82:85], v[212:215], v[70:73]
	v_mfma_f32_16x16x32_bf16 v[82:85], v[146:149], v[224:227], v[66:69]
	s_setprio 0
	s_setprio 1
	v_mfma_f32_16x16x32_bf16 v[30:33], v[150:153], v[182:185], v[30:33]
	v_mfma_f32_16x16x32_bf16 v[30:33], v[154:157], v[192:195], v[30:33]
	v_mfma_f32_16x16x32_bf16 v[26:29], v[178:181], v[192:195], v[26:29]
	v_mfma_f32_16x16x32_bf16 v[26:29], v[158:161], v[182:185], v[26:29]
	v_mfma_f32_16x16x32_bf16 v[18:21], v[158:161], v[196:199], v[18:21]
	v_mfma_f32_16x16x32_bf16 v[18:21], v[178:181], v[200:203], v[18:21]
	v_mfma_f32_16x16x32_bf16 v[22:25], v[154:157], v[200:203], v[22:25]
	v_mfma_f32_16x16x32_bf16 v[22:25], v[150:153], v[196:199], v[22:25]
	v_mfma_f32_16x16x32_bf16 v[14:17], v[150:153], v[204:207], v[14:17]
	v_mfma_f32_16x16x32_bf16 v[14:17], v[154:157], v[208:211], v[14:17]
	v_mfma_f32_16x16x32_bf16 v[10:13], v[178:181], v[208:211], v[10:13]
	v_mfma_f32_16x16x32_bf16 v[10:13], v[158:161], v[204:207], v[10:13]
	v_mfma_f32_16x16x32_bf16 v[2:5], v[158:161], v[212:215], v[2:5]
	v_mfma_f32_16x16x32_bf16 v[2:5], v[178:181], v[224:227], v[2:5]
	v_mfma_f32_16x16x32_bf16 v[6:9], v[154:157], v[224:227], v[6:9]
	v_mfma_f32_16x16x32_bf16 v[6:9], v[150:153], v[212:215], v[6:9]
	s_setprio 0
	s_barrier
	s_add_i32 s30, s30, 2
	s_add_u32 s28, s28, 0x100
	s_addc_u32 s29, s29, 0
	s_cmp_gt_u32 s30, 29
	s_mov_b64 s[0:1], s[2:3]
	s_cbranch_scc0 .LBB0_232
	s_and_b64 vcc, exec, s[44:45]
	s_cbranch_vccz .LBB0_235
	s_barrier

; #define PG8_STAGE(bufoff, gbase, voff) do { const char* gb_ = (const char*)(gbase); asm volatile("" : "+s"(gb_)); _Pragma("unroll") for (int _i = 0; _i < 2; ++_i) { unsigned vo_ = (voff)[_i]; asm volatile("" : "+v"(vo_));        \
;         __builtin_amdgcn_global_load_lds((const unsigned*)(gb_ + vo_), (PG8_LAS unsigned*)(lds + (bufoff) + ldsw + _i * 8192), 16, 0, 0); } } while (0)
; #define PG8_LDA(dst, b, h) do { _Pragma("unroll") for (int m = 0; m < 4; ++m) _Pragma("unroll") for (int k = 0; k < 2; ++k) dst[m][k] = *(const PG8_LAS bf16x8*)(lds + PG8_SA(b, h) + aoff + m * 2048 + k * 1024); } while (0)
; #define PG8_LDB(dst, b, h) do { _Pragma("unroll") for (int n = 0; n < 2; ++n) _Pragma("unroll") for (int k = 0; k < 2; ++k) dst[n][k] = *(const PG8_LAS bf16x8*)(lds + PG8_SB(b, h) + boff + n * 2048 + k * 1024); } while (0)
; #define PG8_MMA(ai, bj, At, Bt) do { __builtin_amdgcn_s_setprio(1); _Pragma("unroll") for (int m = 0; m < 4; ++m) _Pragma("unroll") for (int n = 0; n < 2; ++n) _Pragma("unroll") for (int k = 0; k < 2; ++k) \
;         acc[ai][bj][m][n] = __builtin_amdgcn_mfma_f32_16x16x32_bf16(Bt[n][k], At[m][k], acc[ai][bj][m][n], 0, 0, 0); __builtin_amdgcn_s_setprio(0); } while (0)
; #define PG8_WAIT_V(n) asm volatile("s_waitcnt vmcnt(" #n ")" ::: "memory")
; template <class Epi, class Sched, bool ALIGN_EPI = false, bool SP2 = false>
; __device__ __forceinline__ void gemm_phase(PG8_LAS unsigned char* lds, const Gemm g, const Sched& S, const Epi& E) {
;     ...
;             const bool last = (t == nt - 2);
;             const char* a1 = cA + (size_t)(t + 1) * kstep;
;             const char* a2 = last ? nA : cA + (size_t)(t + 2) * kstep; const char* b2 = last ? nB : cB + (size_t)(t + 2) * kstep;
;             const char* a3 = a2 + kstep; const char* b3 = b2 + kstep;
;             if (last && has_next) S.a_ready(nxt);
;             if constexpr (SP2) {
;             PG8_LDB(B0, 0, 0); PG8_LDB(B1, 0, 1); PG8_SCHED; PG8_LDA(At, 0, 0); PG8_STAGE(PG8_SA(1, 1), a1 + hstep, voffA);
;             PG8_WAIT_V(8); PG8_WAIT_L(0); PG8_BAR; PG8_MMA(0, 0, At, B0); PG8_MMA(0, 1, At, B1); PG8_BAR; PG8_SCHED;
;             PG8_LDA(At, 0, 1); PG8_STAGE(PG8_SB(0, 0), b2, voffB); PG8_STAGE(PG8_SB(0, 1), b2 + hstep, voffB); PG8_STAGE(PG8_SA(0, 0), a2, voffA);
;             PG8_WAIT_V(8); PG8_WAIT_L(0); PG8_BAR; PG8_MMA(1, 0, At, B0); PG8_MMA(1, 1, At, B1); PG8_BAR; PG8_SCHED;
.LBB0_555:
	s_add_u32 s6, s4, 0x100
	s_addc_u32 s7, s5, 0
	s_cmp_eq_u32 s51, 28
	s_cselect_b32 s12, s35, s6
	s_cselect_b32 s13, s34, s7
	s_cselect_b32 s10, s39, s40
	s_cselect_b32 s11, s38, s49
	s_add_u32 s8, s12, 0x80
	s_addc_u32 s9, s13, 0
	s_add_i32 s56, 0, 0x10000
	s_add_i32 s57, 0, 0x14000
	ds_read_b128 v[26:29], v244
	ds_read_b128 v[30:33], v244 offset:1024
	ds_read_b128 v[98:101], v244 offset:2048
	ds_read_b128 v[102:105], v244 offset:3072
	ds_read_b128 v[146:149], v244 offset:16384
	ds_read_b128 v[150:153], v244 offset:17408
	ds_read_b128 v[154:157], v244 offset:18432
	ds_read_b128 v[158:161], v244 offset:19456
	s_add_u32 s4, s4, 0x80080
	s_addc_u32 s5, s5, 0
	ds_read_b128 v[178:181], v210
	ds_read_b128 v[182:185], v210 offset:1024
	ds_read_b128 v[186:189], v210 offset:2048
	ds_read_b128 v[190:193], v210 offset:3072
	ds_read_b128 v[194:197], v210 offset:4096
	ds_read_b128 v[198:201], v210 offset:5120
	ds_read_b128 v[202:205], v210 offset:6144
	ds_read_b128 v[212:215], v210 offset:7168
	s_add_i32 m0, s18, 0xc000
	s_nop 0
	global_load_lds_dwordx4 v1, s[4:5]
	s_add_i32 m0, s18, 0xe000
	s_nop 0
	global_load_lds_dwordx4 v164, s[4:5]
	s_waitcnt vmcnt(8)
	s_waitcnt lgkmcnt(0)
	s_barrier
	s_setprio 1
	s_waitcnt lgkmcnt(0)
	v_mfma_f32_16x16x32_bf16 v[142:145], v[26:29], v[178:181], v[142:145]
	v_mfma_f32_16x16x32_bf16 v[142:145], v[30:33], v[182:185], v[142:145]
	v_mfma_f32_16x16x32_bf16 v[138:141], v[102:105], v[182:185], v[138:141]
	v_mfma_f32_16x16x32_bf16 v[138:141], v[98:101], v[178:181], v[138:141]
	v_mfma_f32_16x16x32_bf16 v[130:133], v[98:101], v[186:189], v[130:133]
	v_mfma_f32_16x16x32_bf16 v[130:133], v[102:105], v[190:193], v[130:133]
	v_mfma_f32_16x16x32_bf16 v[134:137], v[30:33], v[190:193], v[134:137]
	v_mfma_f32_16x16x32_bf16 v[134:137], v[26:29], v[186:189], v[134:137]
	v_mfma_f32_16x16x32_bf16 v[126:129], v[26:29], v[194:197], v[126:129]
	v_mfma_f32_16x16x32_bf16 v[126:129], v[30:33], v[198:201], v[126:129]
	v_mfma_f32_16x16x32_bf16 v[122:125], v[102:105], v[198:201], v[122:125]
	v_mfma_f32_16x16x32_bf16 v[122:125], v[98:101], v[194:197], v[122:125]
	v_mfma_f32_16x16x32_bf16 v[114:117], v[98:101], v[202:205], v[114:117]
	v_mfma_f32_16x16x32_bf16 v[114:117], v[102:105], v[212:215], v[114:117]
	v_mfma_f32_16x16x32_bf16 v[118:121], v[30:33], v[212:215], v[118:121]
	v_mfma_f32_16x16x32_bf16 v[118:121], v[26:29], v[202:205], v[118:121]
	s_setprio 0
	s_setprio 1
	v_mfma_f32_16x16x32_bf16 v[70:73], v[146:149], v[178:181], v[70:73]
	v_mfma_f32_16x16x32_bf16 v[70:73], v[150:153], v[182:185], v[70:73]
	v_mfma_f32_16x16x32_bf16 v[66:69], v[158:161], v[182:185], v[66:69]
	v_mfma_f32_16x16x32_bf16 v[66:69], v[154:157], v[178:181], v[66:69]
	v_mfma_f32_16x16x32_bf16 v[58:61], v[154:157], v[186:189], v[58:61]
	v_mfma_f32_16x16x32_bf16 v[58:61], v[158:161], v[190:193], v[58:61]
	v_mfma_f32_16x16x32_bf16 v[62:65], v[150:153], v[190:193], v[62:65]
	v_mfma_f32_16x16x32_bf16 v[62:65], v[146:149], v[186:189], v[62:65]
	v_mfma_f32_16x16x32_bf16 v[54:57], v[146:149], v[194:197], v[54:57]
	v_mfma_f32_16x16x32_bf16 v[54:57], v[150:153], v[198:201], v[54:57]
	v_mfma_f32_16x16x32_bf16 v[50:53], v[158:161], v[198:201], v[50:53]
	v_mfma_f32_16x16x32_bf16 v[50:53], v[154:157], v[194:197], v[50:53]
	v_mfma_f32_16x16x32_bf16 v[42:45], v[154:157], v[202:205], v[42:45]
	v_mfma_f32_16x16x32_bf16 v[42:45], v[158:161], v[212:215], v[42:45]
	v_mfma_f32_16x16x32_bf16 v[46:49], v[150:153], v[212:215], v[46:49]
	v_mfma_f32_16x16x32_bf16 v[46:49], v[146:149], v[202:205], v[46:49]
	s_setprio 0
	s_barrier
	s_mov_b64 s[4:5], s[10:11]
	s_add_i32 s56, s56, s17
	ds_read_b128 v[178:181], v210 offset:16384
	ds_read_b128 v[182:185], v210 offset:17408
	ds_read_b128 v[186:189], v210 offset:18432
	ds_read_b128 v[190:193], v210 offset:19456
	ds_read_b128 v[194:197], v210 offset:20480
	ds_read_b128 v[198:201], v210 offset:21504
	ds_read_b128 v[202:205], v210 offset:22528
	ds_read_b128 v[212:215], v210 offset:23552
	s_mov_b32 m0, s56
	s_nop 0
	global_load_lds_dwordx4 v162, s[4:5]
	s_add_i32 m0, s56, 0x2000
	s_nop 0
	global_load_lds_dwordx4 v206, s[4:5]
	s_add_u32 s4, s10, 0x80000
	s_addc_u32 s5, s11, 0
	s_add_i32 s56, s57, s17
	s_mov_b32 m0, s56
	s_nop 0
	global_load_lds_dwordx4 v162, s[4:5]
	s_add_i32 m0, s56, 0x2000
	s_nop 0
	global_load_lds_dwordx4 v206, s[4:5]
	s_mov_b64 s[4:5], s[12:13]
	s_mov_b32 m0, s18
	s_nop 0
	global_load_lds_dwordx4 v1, s[4:5]
	s_mov_b32 m0, s19
	s_nop 0
	global_load_lds_dwordx4 v164, s[4:5]
	s_waitcnt vmcnt(8)
	s_waitcnt lgkmcnt(0)
	s_barrier
; #define PG8_STAGE(bufoff, gbase, voff) do { const char* gb_ = (const char*)(gbase); asm volatile("" : "+s"(gb_)); _Pragma("unroll") for (int _i = 0; _i < 2; ++_i) { unsigned vo_ = (voff)[_i]; asm volatile("" : "+v"(vo_));        \
;         __builtin_amdgcn_global_load_lds((const unsigned*)(gb_ + vo_), (PG8_LAS unsigned*)(lds + (bufoff) + ldsw + _i * 8192), 16, 0, 0); } } while (0)
; #define PG8_LDA(dst, b, h) do { _Pragma("unroll") for (int m = 0; m < 4; ++m) _Pragma("unroll") for (int k = 0; k < 2; ++k) dst[m][k] = *(const PG8_LAS bf16x8*)(lds + PG8_SA(b, h) + aoff + m * 2048 + k * 1024); } while (0)
; #define PG8_LDB(dst, b, h) do { _Pragma("unroll") for (int n = 0; n < 2; ++n) _Pragma("unroll") for (int k = 0; k < 2; ++k) dst[n][k] = *(const PG8_LAS bf16x8*)(lds + PG8_SB(b, h) + boff + n * 2048 + k * 1024); } while (0)
; #define PG8_MMA(ai, bj, At, Bt) do { __builtin_amdgcn_s_setprio(1); _Pragma("unroll") for (int m = 0; m < 4; ++m) _Pragma("unroll") for (int n = 0; n < 2; ++n) _Pragma("unroll") for (int k = 0; k < 2; ++k) \
;         acc[ai][bj][m][n] = __builtin_amdgcn_mfma_f32_16x16x32_bf16(Bt[n][k], At[m][k], acc[ai][bj][m][n], 0, 0, 0); __builtin_amdgcn_s_setprio(0); } while (0)
; #define PG8_WAIT_V(n) asm volatile("s_waitcnt vmcnt(" #n ")" ::: "memory")
; #define PG8_WAIT_L(n) asm volatile("s_waitcnt lgkmcnt(" #n ")" ::: "memory")
; #define PG8_BAR __builtin_amdgcn_s_barrier()
; #define PG8_SCHED __builtin_amdgcn_sched_barrier(0)
; template <class Epi, class Sched, bool ALIGN_EPI = false, bool SP2 = false>
; __device__ __forceinline__ void gemm_phase(PG8_LAS unsigned char* lds, const Gemm g, const Sched& S, const Epi& E) {
;     ...
;             PG8_WAIT_V(8); PG8_WAIT_L(0); PG8_BAR; PG8_MMA(1, 0, At, B0); PG8_MMA(1, 1, At, B1); PG8_BAR; PG8_SCHED;
;             PG8_LDB(B0, 1, 0); PG8_LDB(B1, 1, 1); PG8_SCHED; PG8_LDA(At, 1, 0); PG8_STAGE(PG8_SA(0, 1), a2 + hstep, voffA);
;             PG8_WAIT_V(8); PG8_WAIT_L(0); PG8_BAR; PG8_MMA(0, 0, At, B0); PG8_MMA(0, 1, At, B1); PG8_BAR; PG8_SCHED;
	s_setprio 1
	s_waitcnt lgkmcnt(0)
	v_mfma_f32_16x16x32_bf16 v[110:113], v[26:29], v[178:181], v[110:113]
	v_mfma_f32_16x16x32_bf16 v[110:113], v[30:33], v[182:185], v[110:113]
	v_mfma_f32_16x16x32_bf16 v[106:109], v[98:101], v[178:181], v[106:109]
	v_mfma_f32_16x16x32_bf16 v[106:109], v[102:105], v[182:185], v[106:109]
	v_mfma_f32_16x16x32_bf16 v[94:97], v[26:29], v[186:189], v[94:97]
	v_mfma_f32_16x16x32_bf16 v[94:97], v[30:33], v[190:193], v[94:97]
	v_mfma_f32_16x16x32_bf16 v[90:93], v[98:101], v[186:189], v[90:93]
	v_mfma_f32_16x16x32_bf16 v[90:93], v[102:105], v[190:193], v[90:93]
	v_mfma_f32_16x16x32_bf16 v[86:89], v[26:29], v[194:197], v[86:89]
	v_mfma_f32_16x16x32_bf16 v[86:89], v[30:33], v[198:201], v[86:89]
	v_mfma_f32_16x16x32_bf16 v[82:85], v[98:101], v[194:197], v[82:85]
	v_mfma_f32_16x16x32_bf16 v[82:85], v[102:105], v[198:201], v[82:85]
	v_mfma_f32_16x16x32_bf16 v[26:29], v[26:29], v[202:205], v[78:81]
	v_mfma_f32_16x16x32_bf16 v[26:29], v[30:33], v[212:215], v[26:29]
	v_mfma_f32_16x16x32_bf16 v[30:33], v[98:101], v[202:205], v[74:77]
	v_mfma_f32_16x16x32_bf16 v[30:33], v[102:105], v[212:215], v[30:33]
	s_setprio 0
	s_setprio 1
	v_mfma_f32_16x16x32_bf16 v[38:41], v[146:149], v[178:181], v[38:41]
	v_mfma_f32_16x16x32_bf16 v[38:41], v[150:153], v[182:185], v[38:41]
	v_mfma_f32_16x16x32_bf16 v[34:37], v[158:161], v[182:185], v[34:37]
	v_mfma_f32_16x16x32_bf16 v[34:37], v[154:157], v[178:181], v[34:37]
	v_mfma_f32_16x16x32_bf16 v[18:21], v[154:157], v[186:189], v[18:21]
	v_mfma_f32_16x16x32_bf16 v[18:21], v[158:161], v[190:193], v[18:21]
	v_mfma_f32_16x16x32_bf16 v[22:25], v[150:153], v[190:193], v[22:25]
	v_mfma_f32_16x16x32_bf16 v[22:25], v[146:149], v[186:189], v[22:25]
	v_mfma_f32_16x16x32_bf16 v[14:17], v[146:149], v[194:197], v[14:17]
	v_mfma_f32_16x16x32_bf16 v[14:17], v[150:153], v[198:201], v[14:17]
	v_mfma_f32_16x16x32_bf16 v[10:13], v[158:161], v[198:201], v[10:13]
	v_mfma_f32_16x16x32_bf16 v[10:13], v[154:157], v[194:197], v[10:13]
	v_mfma_f32_16x16x32_bf16 v[2:5], v[154:157], v[202:205], v[2:5]
	v_mfma_f32_16x16x32_bf16 v[2:5], v[158:161], v[212:215], v[2:5]
	v_mfma_f32_16x16x32_bf16 v[6:9], v[150:153], v[212:215], v[6:9]
	v_mfma_f32_16x16x32_bf16 v[6:9], v[146:149], v[202:205], v[6:9]
	s_setprio 0
	s_barrier
	s_add_i32 s56, 0, 0x18000
	s_add_i32 s57, 0, 0x1c000
	ds_read_b128 v[74:77], v244 offset:32768
	ds_read_b128 v[78:81], v244 offset:33792
	ds_read_b128 v[98:101], v244 offset:34816
	ds_read_b128 v[102:105], v244 offset:35840
	ds_read_b128 v[146:149], v244 offset:49152
	ds_read_b128 v[150:153], v244 offset:50176
	ds_read_b128 v[154:157], v244 offset:51200
	ds_read_b128 v[158:161], v244 offset:52224
	s_add_u32 s4, s12, 0x80000
	s_addc_u32 s5, s13, 0
	s_mov_b32 m0, s20
	ds_read_b128 v[178:181], v210 offset:32768
	ds_read_b128 v[182:185], v210 offset:33792
	ds_read_b128 v[186:189], v210 offset:34816
	ds_read_b128 v[190:193], v210 offset:35840
	ds_read_b128 v[194:197], v210 offset:36864
	ds_read_b128 v[198:201], v210 offset:37888
	ds_read_b128 v[202:205], v210 offset:38912
	ds_read_b128 v[212:215], v210 offset:39936
	s_nop 0
	global_load_lds_dwordx4 v1, s[4:5]
	s_mov_b32 m0, s21
	s_nop 0
	global_load_lds_dwordx4 v164, s[4:5]
	s_waitcnt vmcnt(8)
	s_waitcnt lgkmcnt(0)
	s_barrier
	s_setprio 1
	s_waitcnt lgkmcnt(0)
	v_mfma_f32_16x16x32_bf16 v[142:145], v[74:77], v[178:181], v[142:145]
	v_mfma_f32_16x16x32_bf16 v[142:145], v[78:81], v[182:185], v[142:145]
	v_mfma_f32_16x16x32_bf16 v[138:141], v[102:105], v[182:185], v[138:141]
	v_mfma_f32_16x16x32_bf16 v[138:141], v[98:101], v[178:181], v[138:141]
	v_mfma_f32_16x16x32_bf16 v[130:133], v[98:101], v[186:189], v[130:133]
	v_mfma_f32_16x16x32_bf16 v[130:133], v[102:105], v[190:193], v[130:133]
	v_mfma_f32_16x16x32_bf16 v[134:137], v[78:81], v[190:193], v[134:137]
	v_mfma_f32_16x16x32_bf16 v[134:137], v[74:77], v[186:189], v[134:137]
	v_mfma_f32_16x16x32_bf16 v[126:129], v[74:77], v[194:197], v[126:129]
	v_mfma_f32_16x16x32_bf16 v[126:129], v[78:81], v[198:201], v[126:129]
	v_mfma_f32_16x16x32_bf16 v[122:125], v[102:105], v[198:201], v[122:125]
	v_mfma_f32_16x16x32_bf16 v[122:125], v[98:101], v[194:197], v[122:125]
	v_mfma_f32_16x16x32_bf16 v[114:117], v[98:101], v[202:205], v[114:117]
	v_mfma_f32_16x16x32_bf16 v[114:117], v[102:105], v[212:215], v[114:117]
	v_mfma_f32_16x16x32_bf16 v[118:121], v[78:81], v[212:215], v[118:121]
	v_mfma_f32_16x16x32_bf16 v[118:121], v[74:77], v[202:205], v[118:121]
	s_setprio 0
	s_setprio 1
	v_mfma_f32_16x16x32_bf16 v[70:73], v[146:149], v[178:181], v[70:73]
	v_mfma_f32_16x16x32_bf16 v[70:73], v[150:153], v[182:185], v[70:73]
	v_mfma_f32_16x16x32_bf16 v[66:69], v[158:161], v[182:185], v[66:69]
	v_mfma_f32_16x16x32_bf16 v[66:69], v[154:157], v[178:181], v[66:69]
	v_mfma_f32_16x16x32_bf16 v[58:61], v[154:157], v[186:189], v[58:61]
	v_mfma_f32_16x16x32_bf16 v[58:61], v[158:161], v[190:193], v[58:61]
	v_mfma_f32_16x16x32_bf16 v[62:65], v[150:153], v[190:193], v[62:65]
	v_mfma_f32_16x16x32_bf16 v[62:65], v[146:149], v[186:189], v[62:65]
	v_mfma_f32_16x16x32_bf16 v[54:57], v[146:149], v[194:197], v[54:57]
	v_mfma_f32_16x16x32_bf16 v[54:57], v[150:153], v[198:201], v[54:57]
	v_mfma_f32_16x16x32_bf16 v[50:53], v[158:161], v[198:201], v[50:53]
	v_mfma_f32_16x16x32_bf16 v[50:53], v[154:157], v[194:197], v[50:53]
	v_mfma_f32_16x16x32_bf16 v[42:45], v[154:157], v[202:205], v[42:45]
	v_mfma_f32_16x16x32_bf16 v[42:45], v[158:161], v[212:215], v[42:45]
	v_mfma_f32_16x16x32_bf16 v[46:49], v[150:153], v[212:215], v[46:49]
	v_mfma_f32_16x16x32_bf16 v[46:49], v[146:149], v[202:205], v[46:49]
	s_setprio 0
	s_barrier
;     __device__ __forceinline__ void operator()(const f32x4 (&acc)[2][2][4][2], const Unit& u, int wr, int wc, int fr, int fq) const {
;         const int row0 = u.pm * BM + wr * 64 + fr, col0 = u.pn * BM + wc * 32 + 8 * fq, b = (u.pm * BM) / rows_per_batch;
;         const float* g = gate + (size_t)b * gate_bstride + col0;
;         float ssq[2][4];
; #pragma unroll
;         for (int ai = 0; ai < 2; ++ai)
; #pragma unroll
;             for (int m = 0; m < 4; ++m) ssq[ai][m] = 0.f;
;         f32x4 gv[2][2], Gv[2][2];
; #pragma unroll
;         for (int bj = 0; bj < 2; ++bj) { gv[bj][0] = *(const f32x4*)(g + bj * HALF); gv[bj][1] = *(const f32x4*)(g + bj * HALF + 4); Gv[bj][0] = (f32x4){0.f, 0.f, 0.f, 0.f}; Gv[bj][1] = (f32x4){0.f, 0.f, 0.f, 0.f};
;             if (Hn) { const float* sc = scnext + (size_t)b * gate_bstride + col0 + bj * HALF;
;                 Gv[bj][0] = *(const f32x4*)(gnext + col0 + bj * HALF) * (1.0f + *(const f32x4*)(sc)); Gv[bj][1] = *(const f32x4*)(gnext + col0 + bj * HALF + 4) * (1.0f + *(const f32x4*)(sc + 4)); } }
; #pragma unroll
;         for (int bj = 0; bj < 2; ++bj) {
;             const f32x4 g0 = gv[bj][0], g1 = gv[bj][1], G0 = Gv[bj][0], G1 = Gv[bj][1];
; #pragma unroll
;             for (int ai = 0; ai < 2; ++ai)
; #pragma unroll
;                 for (int m = 0; m < 4; ++m) { const size_t off = (size_t)(row0 + ai * HALF + m * 16) * 2048 + col0 + bj * HALF;
;                     f32x4 x0 = __builtin_nontemporal_load((const f32x4*)(base + off)), x1 = __builtin_nontemporal_load((const f32x4*)(base + off + 4));
;                     if constexpr (HAS_DIN) { const u32x4 dw = __builtin_nontemporal_load((const u32x4*)(dbuf + off));
;                         x0 += (f32x4){__builtin_bit_cast(float, dw.x << 16), __builtin_bit_cast(float, dw.x & 0xffff0000u), __builtin_bit_cast(float, dw.y << 16), __builtin_bit_cast(float, dw.y & 0xffff0000u)};
; template <class Epi, class Sched, bool ALIGN_EPI = false, bool SP2 = false>
; __device__ __forceinline__ void gemm_phase(PG8_LAS unsigned char* lds, const Gemm g, const Sched& S, const Epi& E) {
;     ...
;             PG8_LDA(At, 1, 1); PG8_STAGE(PG8_SB(1, 0), b3, voffB); PG8_STAGE(PG8_SB(1, 1), b3 + hstep, voffB); PG8_STAGE(PG8_SA(1, 0), a3, voffA);
;             PG8_WAIT_V(8); PG8_WAIT_L(0); PG8_BAR; PG8_MMA(1, 0, At, B0); PG8_MMA(1, 1, At, B1); PG8_BAR; PG8_SCHED;
	s_add_u32 s4, s10, 0x80
	s_addc_u32 s5, s11, 0
	s_add_i32 s12, s56, s17
	ds_read_b128 v[178:181], v210 offset:49152
	ds_read_b128 v[182:185], v210 offset:50176
	ds_read_b128 v[186:189], v210 offset:51200
	ds_read_b128 v[190:193], v210 offset:52224
	ds_read_b128 v[194:197], v210 offset:53248
	ds_read_b128 v[198:201], v210 offset:54272
	ds_read_b128 v[202:205], v210 offset:55296
	ds_read_b128 v[212:215], v210 offset:56320
	s_mov_b32 m0, s12
	s_nop 0
	global_load_lds_dwordx4 v162, s[4:5]
	s_add_i32 m0, s12, 0x2000
	s_nop 0
	global_load_lds_dwordx4 v206, s[4:5]
	s_add_u32 s4, s10, 0x80080
	s_addc_u32 s5, s11, 0
	s_add_i32 s10, s57, s17
	s_mov_b32 m0, s10
	s_nop 0
	global_load_lds_dwordx4 v162, s[4:5]
	s_add_i32 m0, s10, 0x2000
	s_nop 0
	global_load_lds_dwordx4 v206, s[4:5]
	s_mov_b32 m0, s26
	s_nop 0
	global_load_lds_dwordx4 v1, s[8:9]
	s_mov_b32 m0, s27
	s_nop 0
	global_load_lds_dwordx4 v164, s[8:9]
	s_waitcnt vmcnt(8)
	s_waitcnt lgkmcnt(0)
	s_barrier
	s_setprio 1
	s_waitcnt lgkmcnt(0)
	v_mfma_f32_16x16x32_bf16 v[110:113], v[74:77], v[178:181], v[110:113]
	v_mfma_f32_16x16x32_bf16 v[110:113], v[78:81], v[182:185], v[110:113]
	v_mfma_f32_16x16x32_bf16 v[94:97], v[74:77], v[186:189], v[94:97]
	v_mfma_f32_16x16x32_bf16 v[94:97], v[78:81], v[190:193], v[94:97]
	v_mfma_f32_16x16x32_bf16 v[86:89], v[74:77], v[194:197], v[86:89]
	v_mfma_f32_16x16x32_bf16 v[86:89], v[78:81], v[198:201], v[86:89]
	v_mfma_f32_16x16x32_bf16 v[26:29], v[74:77], v[202:205], v[26:29]
	v_mfma_f32_16x16x32_bf16 v[78:81], v[78:81], v[212:215], v[26:29]
	v_mfma_f32_16x16x32_bf16 v[106:109], v[98:101], v[178:181], v[106:109]
	v_mfma_f32_16x16x32_bf16 v[106:109], v[102:105], v[182:185], v[106:109]
	v_mfma_f32_16x16x32_bf16 v[90:93], v[98:101], v[186:189], v[90:93]
	v_mfma_f32_16x16x32_bf16 v[90:93], v[102:105], v[190:193], v[90:93]
	v_mfma_f32_16x16x32_bf16 v[82:85], v[98:101], v[194:197], v[82:85]
	v_mfma_f32_16x16x32_bf16 v[82:85], v[102:105], v[198:201], v[82:85]
	v_mfma_f32_16x16x32_bf16 v[26:29], v[98:101], v[202:205], v[30:33]
	v_mfma_f32_16x16x32_bf16 v[74:77], v[102:105], v[212:215], v[26:29]
	s_setprio 0
	s_setprio 1
	v_mfma_f32_16x16x32_bf16 v[26:29], v[146:149], v[178:181], v[38:41]
	v_mfma_f32_16x16x32_bf16 v[38:41], v[150:153], v[182:185], v[26:29]
	v_mfma_f32_16x16x32_bf16 v[26:29], v[154:157], v[178:181], v[34:37]
	v_mfma_f32_16x16x32_bf16 v[34:37], v[158:161], v[182:185], v[26:29]
	v_mfma_f32_16x16x32_bf16 v[22:25], v[146:149], v[186:189], v[22:25]
	v_mfma_f32_16x16x32_bf16 v[22:25], v[150:153], v[190:193], v[22:25]
	v_mfma_f32_16x16x32_bf16 v[18:21], v[154:157], v[186:189], v[18:21]
	v_mfma_f32_16x16x32_bf16 v[18:21], v[158:161], v[190:193], v[18:21]
	v_mfma_f32_16x16x32_bf16 v[14:17], v[146:149], v[194:197], v[14:17]
	v_mfma_f32_16x16x32_bf16 v[14:17], v[150:153], v[198:201], v[14:17]
	v_mfma_f32_16x16x32_bf16 v[10:13], v[154:157], v[194:197], v[10:13]
	v_mfma_f32_16x16x32_bf16 v[10:13], v[158:161], v[198:201], v[10:13]
	v_mfma_f32_16x16x32_bf16 v[6:9], v[146:149], v[202:205], v[6:9]
	v_mfma_f32_16x16x32_bf16 v[6:9], v[150:153], v[212:215], v[6:9]
	v_mfma_f32_16x16x32_bf16 v[2:5], v[154:157], v[202:205], v[2:5]
	v_mfma_f32_16x16x32_bf16 v[2:5], v[158:161], v[212:215], v[2:5]
	s_setprio 0
	s_barrier
	s_add_i32 s51, s51, 2
	s_add_u32 s40, s40, 0x100
	s_addc_u32 s49, s49, 0
	s_cmp_gt_u32 s51, 29
	s_mov_b64 s[4:5], s[6:7]
	s_cbranch_scc0 .LBB0_555
	s_ashr_i32 s4, s29, 31
	s_lshr_b32 s4, s4, 27
	s_add_i32 s4, s29, s4
	s_ashr_i32 s4, s4, 5
	v_lshl_or_b32 v148, s33, 8, v209
	s_mul_i32 s7, s4, 0xc000
	v_ashrrev_i32_e32 v149, 31, v148
	s_mul_hi_i32 s6, s4, 0xc000
	s_add_u32 s4, s22, s7
	s_addc_u32 s5, s23, s6
	v_lshlrev_b64 v[26:27], 2, v[148:149]
	v_lshl_add_u64 v[146:147], s[4:5], 0, v[26:27]
	s_add_u32 s4, s24, s7
	s_addc_u32 s5, s25, s6
	v_lshl_add_u64 v[160:161], s[4:5], 0, v[26:27]
	v_lshl_add_u64 v[178:179], s[46:47], 0, v[26:27]
	global_load_dwordx4 v[98:101], v[146:147], off offset:16
	global_load_dwordx4 v[102:105], v[146:147], off
	global_load_dwordx4 v[26:29], v[178:179], off offset:16
	global_load_dwordx4 v[30:33], v[178:179], off
	global_load_dwordx4 v[150:153], v[160:161], off offset:16
	global_load_dwordx4 v[154:157], v[160:161], off
	s_mov_b64 s[4:5], 0x40000
	s_waitcnt vmcnt(0)
	v_pk_mul_f32 v[188:189], v[140:141], v[100:101]
	v_pk_mul_f32 v[142:143], v[142:143], v[102:103]
	v_pk_mul_f32 v[144:145], v[144:145], v[104:105]
	v_pk_mul_f32 v[140:141], v[138:139], v[98:99]
	v_pk_mul_f32 v[136:137], v[136:137], v[104:105]
	v_pk_add_f32 v[156:157], v[156:157], 1.0 op_sel_hi:[1,0]
	v_pk_add_f32 v[154:155], v[154:155], 1.0 op_sel_hi:[1,0]
	v_pk_mul_f32 v[198:199], v[32:33], v[156:157]
	v_pk_mul_f32 v[200:201], v[30:31], v[154:155]
	v_pk_add_f32 v[30:31], v[152:153], 1.0 op_sel_hi:[1,0]
	v_pk_add_f32 v[32:33], v[150:151], 1.0 op_sel_hi:[1,0]
	v_pk_mul_f32 v[202:203], v[28:29], v[30:31]
	v_pk_mul_f32 v[204:205], v[26:27], v[32:33]
	global_load_dwordx4 v[26:29], v[146:147], off offset:528
	global_load_dwordx4 v[30:33], v[146:147], off offset:512
	global_load_dwordx4 v[156:159], v[178:179], off offset:528
	global_load_dwordx4 v[152:155], v[178:179], off offset:512
	s_nop 0
	global_load_dwordx4 v[178:181], v[160:161], off offset:528
	global_load_dwordx4 v[182:185], v[160:161], off offset:512
	v_pk_mul_f32 v[134:135], v[134:135], v[102:103]
	v_pk_mul_f32 v[130:131], v[130:131], v[98:99]
	v_pk_mul_f32 v[132:133], v[132:133], v[100:101]
	v_pk_mul_f32 v[128:129], v[128:129], v[104:105]
	v_pk_mul_f32 v[126:127], v[126:127], v[102:103]
	v_pk_mul_f32 v[122:123], v[122:123], v[98:99]
	v_pk_mul_f32 v[124:125], v[124:125], v[100:101]
	v_pk_mul_f32 v[120:121], v[120:121], v[104:105]
	v_pk_mul_f32 v[118:119], v[118:119], v[102:103]
	v_pk_mul_f32 v[114:115], v[114:115], v[98:99]
	v_pk_mul_f32 v[116:117], v[116:117], v[100:101]
	v_pk_mul_f32 v[112:113], v[112:113], v[104:105]
	v_pk_mul_f32 v[110:111], v[110:111], v[102:103]
	v_pk_mul_f32 v[106:107], v[106:107], v[98:99]
	v_pk_mul_f32 v[108:109], v[108:109], v[100:101]
	v_pk_mul_f32 v[96:97], v[96:97], v[104:105]
	v_pk_mul_f32 v[94:95], v[94:95], v[102:103]
	v_pk_mul_f32 v[90:91], v[90:91], v[98:99]
	v_pk_mul_f32 v[92:93], v[92:93], v[100:101]
	v_pk_mul_f32 v[88:89], v[88:89], v[104:105]
	v_pk_mul_f32 v[86:87], v[86:87], v[102:103]
	v_pk_mul_f32 v[82:83], v[82:83], v[98:99]
	v_pk_mul_f32 v[84:85], v[84:85], v[100:101]
	v_pk_mul_f32 v[80:81], v[80:81], v[104:105]
	v_pk_mul_f32 v[78:79], v[78:79], v[102:103]
	v_pk_mul_f32 v[74:75], v[74:75], v[98:99]
	v_pk_mul_f32 v[76:77], v[76:77], v[100:101]
	s_waitcnt vmcnt(5)
; __device__ __forceinline__ unsigned cvt_pk_bf16(float lo, float hi) { unsigned r; asm volatile("v_cvt_pk_bf16_f32 %0, %1, %2" : "=v"(r) : "v"(lo), "v"(hi)); return r; }
;     __device__ __forceinline__ void operator()(const f32x4 (&acc)[2][2][4][2], const Unit& u, int wr, int wc, int fr, int fq) const {
;     ...
;                 for (int m = 0; m < 4; ++m) { const size_t off = (size_t)(row0 + ai * HALF + m * 16) * 2048 + col0 + bj * HALF;
;                     f32x4 x0 = __builtin_nontemporal_load((const f32x4*)(base + off)), x1 = __builtin_nontemporal_load((const f32x4*)(base + off + 4));
;                     if constexpr (HAS_DIN) { const u32x4 dw = __builtin_nontemporal_load((const u32x4*)(dbuf + off));
;                         x0 += (f32x4){__builtin_bit_cast(float, dw.x << 16), __builtin_bit_cast(float, dw.x & 0xffff0000u), __builtin_bit_cast(float, dw.y << 16), __builtin_bit_cast(float, dw.y & 0xffff0000u)};
;                         x1 += (f32x4){__builtin_bit_cast(float, dw.z << 16), __builtin_bit_cast(float, dw.z & 0xffff0000u), __builtin_bit_cast(float, dw.w << 16), __builtin_bit_cast(float, dw.w & 0xffff0000u)}; }
;                     f32x4 o0, o1;
;                     if constexpr (OUT_DELTA) { const f32x4 d0 = g0 * acc[ai][bj][m][0], d1 = g1 * acc[ai][bj][m][1];
;                         u32x4 w; w.x = cvt_pk_bf16(d0[0], d0[1]); w.y = cvt_pk_bf16(d0[2], d0[3]); w.z = cvt_pk_bf16(d1[0], d1[1]); w.w = cvt_pk_bf16(d1[2], d1[3]);
;                         *(u32x4*)(dbuf + off) = w;
;                         o0 = x0 + (f32x4){__builtin_bit_cast(float, w.x << 16), __builtin_bit_cast(float, w.x & 0xffff0000u), __builtin_bit_cast(float, w.y << 16), __builtin_bit_cast(float, w.y & 0xffff0000u)};
;                         o1 = x1 + (f32x4){__builtin_bit_cast(float, w.z << 16), __builtin_bit_cast(float, w.z & 0xffff0000u), __builtin_bit_cast(float, w.w << 16), __builtin_bit_cast(float, w.w & 0xffff0000u)}; }
;                     else { o0 = x0 + g0 * acc[ai][bj][m][0]; o1 = x1 + g1 * acc[ai][bj][m][1]; *(f32x4*)(out + off) = o0; *(f32x4*)(out + off + 4) = o1; }
;                     if (Hn) { const f32x4 h0 = o0 * G0, h1 = o1 * G1;
;                         u32x4 w; w.x = cvt_pk_bf16(h0[0], h0[1]); w.y = cvt_pk_bf16(h0[2], h0[3]); w.z = cvt_pk_bf16(h1[0], h1[1]); w.w = cvt_pk_bf16(h1[2], h1[3]);
;                         *(u32x4*)(Hn + off) = w;
	v_pk_mul_f32 v[58:59], v[58:59], v[26:27]
	s_waitcnt vmcnt(4)
	v_pk_mul_f32 v[72:73], v[72:73], v[32:33]
	v_pk_mul_f32 v[70:71], v[70:71], v[30:31]
	v_pk_mul_f32 v[64:65], v[64:65], v[32:33]
	v_pk_mul_f32 v[62:63], v[62:63], v[30:31]
	s_waitcnt vmcnt(0)
	v_pk_add_f32 v[146:147], v[184:185], 1.0 op_sel_hi:[1,0]
	v_pk_add_f32 v[160:161], v[182:183], 1.0 op_sel_hi:[1,0]
	v_pk_mul_f32 v[150:151], v[154:155], v[146:147]
	v_pk_add_f32 v[146:147], v[180:181], 1.0 op_sel_hi:[1,0]
	v_pk_mul_f32 v[152:153], v[152:153], v[160:161]
	v_pk_mul_f32 v[154:155], v[158:159], v[146:147]
	v_lshl_add_u32 v146, s29, 8, v207
	v_ashrrev_i32_e32 v147, 31, v146
	v_lshlrev_b64 v[184:185], 11, v[146:147]
	v_lshl_add_u64 v[186:187], v[184:185], 0, v[148:149]
	v_pk_add_f32 v[160:161], v[178:179], 1.0 op_sel_hi:[1,0]
	v_lshl_add_u64 v[178:179], v[186:187], 2, s[44:45]
	v_pk_mul_f32 v[156:157], v[156:157], v[160:161]
	global_load_dwordx4 v[158:161], v[178:179], off nt
	global_load_dwordx4 v[180:183], v[178:179], off offset:16 nt
	v_cvt_pk_bf16_f32 v138, v142, v143
	v_lshlrev_b64 v[142:143], 1, v[186:187]
	v_cvt_pk_bf16_f32 v139, v144, v145
	v_cvt_pk_bf16_f32 v140, v140, v141
	v_cvt_pk_bf16_f32 v141, v188, v189
	v_lshl_add_u64 v[144:145], s[90:91], 0, v[142:143]
	global_store_dwordx4 v[144:145], v[138:141], off
	v_lshlrev_b32_e32 v144, 16, v140
	v_and_b32_e32 v145, 0xffff0000, v140
	v_lshlrev_b32_e32 v140, 16, v141
	v_and_b32_e32 v141, 0xffff0000, v141
	v_lshl_add_u64 v[142:143], s[96:97], 0, v[142:143]
	v_pk_mul_f32 v[60:61], v[60:61], v[28:29]
	v_pk_mul_f32 v[56:57], v[56:57], v[32:33]
	v_pk_mul_f32 v[54:55], v[54:55], v[30:31]
	v_pk_mul_f32 v[50:51], v[50:51], v[26:27]
	v_pk_mul_f32 v[52:53], v[52:53], v[28:29]
	v_pk_mul_f32 v[48:49], v[48:49], v[32:33]
	v_pk_mul_f32 v[46:47], v[46:47], v[30:31]
	v_pk_mul_f32 v[42:43], v[42:43], v[26:27]
	v_pk_mul_f32 v[44:45], v[44:45], v[28:29]
	v_pk_mul_f32 v[40:41], v[40:41], v[32:33]
	v_pk_mul_f32 v[38:39], v[38:39], v[30:31]
	v_pk_mul_f32 v[34:35], v[34:35], v[26:27]
	v_pk_mul_f32 v[36:37], v[36:37], v[28:29]
	v_pk_mul_f32 v[24:25], v[24:25], v[32:33]
	v_pk_mul_f32 v[22:23], v[22:23], v[30:31]
	v_pk_mul_f32 v[18:19], v[18:19], v[26:27]
	v_pk_mul_f32 v[20:21], v[20:21], v[28:29]
	v_pk_mul_f32 v[16:17], v[16:17], v[32:33]
	v_pk_mul_f32 v[14:15], v[14:15], v[30:31]
	v_pk_mul_f32 v[10:11], v[10:11], v[26:27]
	v_pk_mul_f32 v[12:13], v[12:13], v[28:29]
	v_pk_mul_f32 v[8:9], v[8:9], v[32:33]
	v_pk_mul_f32 v[6:7], v[6:7], v[30:31]
	v_pk_mul_f32 v[2:3], v[2:3], v[26:27]
	v_pk_mul_f32 v[4:5], v[4:5], v[28:29]
	s_waitcnt vmcnt(1)
	v_pk_add_f32 v[182:183], v[182:183], v[140:141]
	v_lshlrev_b32_e32 v140, 16, v138
	v_and_b32_e32 v141, 0xffff0000, v138
	v_lshlrev_b32_e32 v138, 16, v139
	v_and_b32_e32 v139, 0xffff0000, v139
	v_pk_add_f32 v[158:159], v[158:159], v[140:141]
	v_pk_add_f32 v[160:161], v[160:161], v[138:139]
	v_pk_mul_f32 v[138:139], v[200:201], v[158:159]
	v_pk_add_f32 v[144:145], v[180:181], v[144:145]
	v_pk_mul_f32 v[140:141], v[198:199], v[160:161]
	v_cvt_pk_bf16_f32 v138, v138, v139
	v_pk_mul_f32 v[180:181], v[202:203], v[182:183]
	v_cvt_pk_bf16_f32 v139, v140, v141
	v_pk_mul_f32 v[186:187], v[204:205], v[144:145]
	s_nop 0
	v_cvt_pk_bf16_f32 v140, v186, v187
	v_cvt_pk_bf16_f32 v141, v180, v181
	global_store_dwordx4 v[142:143], v[138:141], off
	s_nop 1
	v_mul_f32_e32 v138, v159, v159
	v_mul_f32_e32 v139, v161, v161
	v_fmac_f32_e32 v138, v158, v158
	v_fmac_f32_e32 v139, v160, v160
	v_add_f32_e32 v138, v138, v139
	v_mul_f32_e32 v139, v145, v145
	v_mul_f32_e32 v140, v183, v183
	v_fmac_f32_e32 v139, v144, v144
	v_fmac_f32_e32 v140, v182, v182
	v_add_f32_e32 v139, v139, v140
	v_add_f32_e32 v211, v138, v139
	v_or_b32_e32 v138, 16, v146
	v_ashrrev_i32_e32 v139, 31, v138
	v_lshlrev_b64 v[140:141], 11, v[138:139]
	v_lshl_add_u64 v[180:181], v[140:141], 0, v[148:149]
	v_lshl_add_u64 v[138:139], v[180:181], 2, s[44:45]
	global_load_dwordx4 v[142:145], v[138:139], off nt
	global_load_dwordx4 v[158:161], v[138:139], off offset:16 nt
	v_lshlrev_b64 v[180:181], 1, v[180:181]
	v_cvt_pk_bf16_f32 v134, v134, v135
	v_cvt_pk_bf16_f32 v135, v136, v137
	v_cvt_pk_bf16_f32 v136, v130, v131
	v_cvt_pk_bf16_f32 v137, v132, v133
	v_lshl_add_u64 v[130:131], s[90:91], 0, v[180:181]
	global_store_dwordx4 v[130:131], v[134:137], off
	v_lshlrev_b32_e32 v132, 16, v136
	v_and_b32_e32 v133, 0xffff0000, v136
	v_lshlrev_b32_e32 v130, 16, v137
	v_and_b32_e32 v131, 0xffff0000, v137
	v_lshlrev_b32_e32 v136, 16, v134
	v_and_b32_e32 v137, 0xffff0000, v134
	v_lshlrev_b32_e32 v134, 16, v135
	v_and_b32_e32 v135, 0xffff0000, v135
	s_waitcnt vmcnt(2)
	v_pk_add_f32 v[134:135], v[144:145], v[134:135]
	s_waitcnt vmcnt(1)
	v_pk_add_f32 v[130:131], v[160:161], v[130:131]
	v_pk_add_f32 v[136:137], v[142:143], v[136:137]
	v_pk_add_f32 v[132:133], v[158:159], v[132:133]
	v_pk_mul_f32 v[144:145], v[198:199], v[134:135]
	v_pk_mul_f32 v[142:143], v[200:201], v[136:137]
	v_pk_mul_f32 v[158:159], v[202:203], v[130:131]
	v_pk_mul_f32 v[160:161], v[204:205], v[132:133]
	v_cvt_pk_bf16_f32 v142, v142, v143
	v_cvt_pk_bf16_f32 v143, v144, v145
	s_nop 0
	v_cvt_pk_bf16_f32 v144, v160, v161
	v_cvt_pk_bf16_f32 v145, v158, v159
	v_lshl_add_u64 v[158:159], s[96:97], 0, v[180:181]
	global_store_dwordx4 v[158:159], v[142:145], off
	s_nop 1
	v_or_b32_e32 v142, 32, v146
	v_ashrrev_i32_e32 v143, 31, v142
	v_lshlrev_b64 v[144:145], 11, v[142:143]
	v_lshl_add_u64 v[186:187], v[144:145], 0, v[148:149]
	v_lshl_add_u64 v[142:143], v[186:187], 2, s[44:45]
	global_load_dwordx4 v[158:161], v[142:143], off nt
	global_load_dwordx4 v[180:183], v[142:143], off offset:16 nt
	v_lshlrev_b64 v[186:187], 1, v[186:187]
	v_cvt_pk_bf16_f32 v126, v126, v127
	v_cvt_pk_bf16_f32 v127, v128, v129
	v_cvt_pk_bf16_f32 v128, v122, v123
	v_cvt_pk_bf16_f32 v129, v124, v125
	v_lshl_add_u64 v[122:123], s[90:91], 0, v[186:187]
	global_store_dwordx4 v[122:123], v[126:129], off
	v_lshlrev_b32_e32 v124, 16, v128
	v_and_b32_e32 v125, 0xffff0000, v128
	v_lshlrev_b32_e32 v122, 16, v129
	v_and_b32_e32 v123, 0xffff0000, v129
	v_lshlrev_b32_e32 v128, 16, v126
	v_and_b32_e32 v129, 0xffff0000, v126
	v_lshlrev_b32_e32 v126, 16, v127
	v_and_b32_e32 v127, 0xffff0000, v127
	s_waitcnt vmcnt(2)
; __device__ __forceinline__ unsigned cvt_pk_bf16(float lo, float hi) { unsigned r; asm volatile("v_cvt_pk_bf16_f32 %0, %1, %2" : "=v"(r) : "v"(lo), "v"(hi)); return r; }
;     __device__ __forceinline__ void operator()(const f32x4 (&acc)[2][2][4][2], const Unit& u, int wr, int wc, int fr, int fq) const {
;     ...
;                 for (int m = 0; m < 4; ++m) { const size_t off = (size_t)(row0 + ai * HALF + m * 16) * 2048 + col0 + bj * HALF;
;                     f32x4 x0 = __builtin_nontemporal_load((const f32x4*)(base + off)), x1 = __builtin_nontemporal_load((const f32x4*)(base + off + 4));
;                     if constexpr (HAS_DIN) { const u32x4 dw = __builtin_nontemporal_load((const u32x4*)(dbuf + off));
;                         x0 += (f32x4){__builtin_bit_cast(float, dw.x << 16), __builtin_bit_cast(float, dw.x & 0xffff0000u), __builtin_bit_cast(float, dw.y << 16), __builtin_bit_cast(float, dw.y & 0xffff0000u)};
;                         x1 += (f32x4){__builtin_bit_cast(float, dw.z << 16), __builtin_bit_cast(float, dw.z & 0xffff0000u), __builtin_bit_cast(float, dw.w << 16), __builtin_bit_cast(float, dw.w & 0xffff0000u)}; }
;                     f32x4 o0, o1;
;                     if constexpr (OUT_DELTA) { const f32x4 d0 = g0 * acc[ai][bj][m][0], d1 = g1 * acc[ai][bj][m][1];
;                         u32x4 w; w.x = cvt_pk_bf16(d0[0], d0[1]); w.y = cvt_pk_bf16(d0[2], d0[3]); w.z = cvt_pk_bf16(d1[0], d1[1]); w.w = cvt_pk_bf16(d1[2], d1[3]);
;                         *(u32x4*)(dbuf + off) = w;
;                         o0 = x0 + (f32x4){__builtin_bit_cast(float, w.x << 16), __builtin_bit_cast(float, w.x & 0xffff0000u), __builtin_bit_cast(float, w.y << 16), __builtin_bit_cast(float, w.y & 0xffff0000u)};
;                         o1 = x1 + (f32x4){__builtin_bit_cast(float, w.z << 16), __builtin_bit_cast(float, w.z & 0xffff0000u), __builtin_bit_cast(float, w.w << 16), __builtin_bit_cast(float, w.w & 0xffff0000u)}; }
;                     else { o0 = x0 + g0 * acc[ai][bj][m][0]; o1 = x1 + g1 * acc[ai][bj][m][1]; *(f32x4*)(out + off) = o0; *(f32x4*)(out + off + 4) = o1; }
;                     if (Hn) { const f32x4 h0 = o0 * G0, h1 = o1 * G1;
;                         u32x4 w; w.x = cvt_pk_bf16(h0[0], h0[1]); w.y = cvt_pk_bf16(h0[2], h0[3]); w.z = cvt_pk_bf16(h1[0], h1[1]); w.w = cvt_pk_bf16(h1[2], h1[3]);
;                         *(u32x4*)(Hn + off) = w;
	v_pk_add_f32 v[126:127], v[160:161], v[126:127]
	s_waitcnt vmcnt(1)
	v_pk_add_f32 v[122:123], v[182:183], v[122:123]
	v_pk_add_f32 v[128:129], v[158:159], v[128:129]
	v_pk_add_f32 v[124:125], v[180:181], v[124:125]
	v_pk_mul_f32 v[160:161], v[198:199], v[126:127]
	v_pk_mul_f32 v[158:159], v[200:201], v[128:129]
	v_pk_mul_f32 v[180:181], v[202:203], v[122:123]
	v_pk_mul_f32 v[182:183], v[204:205], v[124:125]
	v_cvt_pk_bf16_f32 v158, v158, v159
	v_cvt_pk_bf16_f32 v159, v160, v161
	s_nop 0
	v_cvt_pk_bf16_f32 v160, v182, v183
	v_cvt_pk_bf16_f32 v161, v180, v181
	v_lshl_add_u64 v[180:181], s[96:97], 0, v[186:187]
	global_store_dwordx4 v[180:181], v[158:161], off
	s_nop 1
	v_or_b32_e32 v158, 48, v146
	v_ashrrev_i32_e32 v159, 31, v158
	v_lshlrev_b64 v[160:161], 11, v[158:159]
	v_lshl_add_u64 v[190:191], v[160:161], 0, v[148:149]
	v_lshl_add_u64 v[158:159], v[190:191], 2, s[44:45]
	global_load_dwordx4 v[180:183], v[158:159], off nt
	global_load_dwordx4 v[186:189], v[158:159], off offset:16 nt
	v_lshlrev_b64 v[190:191], 1, v[190:191]
	v_cvt_pk_bf16_f32 v118, v118, v119
	v_cvt_pk_bf16_f32 v119, v120, v121
	v_cvt_pk_bf16_f32 v120, v114, v115
	v_cvt_pk_bf16_f32 v121, v116, v117
	v_lshl_add_u64 v[114:115], s[90:91], 0, v[190:191]
	global_store_dwordx4 v[114:115], v[118:121], off
	v_lshlrev_b32_e32 v116, 16, v120
	v_and_b32_e32 v117, 0xffff0000, v120
	v_lshlrev_b32_e32 v114, 16, v121
	v_and_b32_e32 v115, 0xffff0000, v121
	v_lshlrev_b32_e32 v120, 16, v118
	v_and_b32_e32 v121, 0xffff0000, v118
	v_lshlrev_b32_e32 v118, 16, v119
	v_and_b32_e32 v119, 0xffff0000, v119
	s_waitcnt vmcnt(2)
	v_pk_add_f32 v[118:119], v[182:183], v[118:119]
	s_waitcnt vmcnt(1)
	v_pk_add_f32 v[114:115], v[188:189], v[114:115]
	v_pk_add_f32 v[120:121], v[180:181], v[120:121]
	v_pk_add_f32 v[116:117], v[186:187], v[116:117]
	v_pk_mul_f32 v[182:183], v[198:199], v[118:119]
	v_pk_mul_f32 v[180:181], v[200:201], v[120:121]
	v_pk_mul_f32 v[186:187], v[202:203], v[114:115]
	v_pk_mul_f32 v[188:189], v[204:205], v[116:117]
	v_cvt_pk_bf16_f32 v180, v180, v181
	v_cvt_pk_bf16_f32 v181, v182, v183
	s_nop 0
	v_cvt_pk_bf16_f32 v182, v188, v189
	v_cvt_pk_bf16_f32 v183, v186, v187
	v_lshl_add_u64 v[186:187], s[96:97], 0, v[190:191]
	global_store_dwordx4 v[186:187], v[180:183], off
	s_nop 1
	v_lshl_add_u64 v[182:183], v[184:185], 0, s[4:5]
	v_lshl_add_u64 v[194:195], v[182:183], 0, v[148:149]
	v_lshl_add_u64 v[180:181], v[194:195], 2, s[44:45]
	global_load_dwordx4 v[186:189], v[180:181], off nt
	global_load_dwordx4 v[190:193], v[180:181], off offset:16 nt
	v_lshlrev_b64 v[194:195], 1, v[194:195]
	v_cvt_pk_bf16_f32 v110, v110, v111
	v_cvt_pk_bf16_f32 v111, v112, v113
	v_cvt_pk_bf16_f32 v112, v106, v107
	v_cvt_pk_bf16_f32 v113, v108, v109
	v_lshl_add_u64 v[106:107], s[90:91], 0, v[194:195]
	global_store_dwordx4 v[106:107], v[110:113], off
	v_lshlrev_b32_e32 v108, 16, v112
	v_and_b32_e32 v109, 0xffff0000, v112
	v_lshlrev_b32_e32 v106, 16, v113
	v_and_b32_e32 v107, 0xffff0000, v113
	v_lshlrev_b32_e32 v112, 16, v110
	v_and_b32_e32 v113, 0xffff0000, v110
	v_lshlrev_b32_e32 v110, 16, v111
	v_and_b32_e32 v111, 0xffff0000, v111
	s_mov_b64 s[4:5], 0x48000
	s_waitcnt vmcnt(2)
	v_pk_add_f32 v[110:111], v[188:189], v[110:111]
	s_waitcnt vmcnt(1)
	v_pk_add_f32 v[106:107], v[192:193], v[106:107]
	v_pk_add_f32 v[112:113], v[186:187], v[112:113]
	v_pk_add_f32 v[108:109], v[190:191], v[108:109]
	v_pk_mul_f32 v[188:189], v[198:199], v[110:111]
	v_pk_mul_f32 v[186:187], v[200:201], v[112:113]
	v_pk_mul_f32 v[190:191], v[202:203], v[106:107]
	v_pk_mul_f32 v[192:193], v[204:205], v[108:109]
	v_cvt_pk_bf16_f32 v186, v186, v187
	v_cvt_pk_bf16_f32 v187, v188, v189
	s_nop 0
	v_cvt_pk_bf16_f32 v188, v192, v193
	v_cvt_pk_bf16_f32 v189, v190, v191
	v_lshl_add_u64 v[190:191], s[96:97], 0, v[194:195]
	global_store_dwordx4 v[190:191], v[186:189], off
	s_nop 1
	v_lshl_add_u64 v[188:189], v[184:185], 0, s[4:5]
	v_lshl_add_u64 v[212:213], v[188:189], 0, v[148:149]
	v_lshl_add_u64 v[186:187], v[212:213], 2, s[44:45]
	global_load_dwordx4 v[190:193], v[186:187], off nt
	global_load_dwordx4 v[194:197], v[186:187], off offset:16 nt
	v_lshlrev_b64 v[212:213], 1, v[212:213]
	v_cvt_pk_bf16_f32 v94, v94, v95
	v_cvt_pk_bf16_f32 v95, v96, v97
	v_cvt_pk_bf16_f32 v96, v90, v91
	v_cvt_pk_bf16_f32 v97, v92, v93
	v_lshl_add_u64 v[90:91], s[90:91], 0, v[212:213]
	global_store_dwordx4 v[90:91], v[94:97], off
	v_lshlrev_b32_e32 v92, 16, v96
	v_and_b32_e32 v93, 0xffff0000, v96
	v_lshlrev_b32_e32 v90, 16, v97
	v_and_b32_e32 v91, 0xffff0000, v97
	v_lshlrev_b32_e32 v96, 16, v94
	v_and_b32_e32 v97, 0xffff0000, v94
	v_lshlrev_b32_e32 v94, 16, v95
	v_and_b32_e32 v95, 0xffff0000, v95
	s_mov_b64 s[4:5], 0x50000
	s_waitcnt vmcnt(2)
	v_pk_add_f32 v[94:95], v[192:193], v[94:95]
	s_waitcnt vmcnt(1)
	v_pk_add_f32 v[90:91], v[196:197], v[90:91]
	v_pk_add_f32 v[96:97], v[190:191], v[96:97]
	v_pk_add_f32 v[92:93], v[194:195], v[92:93]
	v_pk_mul_f32 v[192:193], v[198:199], v[94:95]
	v_pk_mul_f32 v[190:191], v[200:201], v[96:97]
	v_pk_mul_f32 v[194:195], v[202:203], v[90:91]
	v_pk_mul_f32 v[196:197], v[204:205], v[92:93]
	v_cvt_pk_bf16_f32 v190, v190, v191
	v_cvt_pk_bf16_f32 v191, v192, v193
	s_nop 0
	v_cvt_pk_bf16_f32 v192, v196, v197
	v_cvt_pk_bf16_f32 v193, v194, v195
	v_lshl_add_u64 v[194:195], s[96:97], 0, v[212:213]
	global_store_dwordx4 v[194:195], v[190:193], off
	s_nop 1
	v_lshl_add_u64 v[192:193], v[184:185], 0, s[4:5]
	v_lshl_add_u64 v[220:221], v[192:193], 0, v[148:149]
	v_lshl_add_u64 v[190:191], v[220:221], 2, s[44:45]
	global_load_dwordx4 v[194:197], v[190:191], off nt
	global_load_dwordx4 v[212:215], v[190:191], off offset:16 nt
	v_lshlrev_b64 v[220:221], 1, v[220:221]
	v_cvt_pk_bf16_f32 v86, v86, v87
	v_cvt_pk_bf16_f32 v87, v88, v89
	v_cvt_pk_bf16_f32 v88, v82, v83
	v_cvt_pk_bf16_f32 v89, v84, v85
	v_lshl_add_u64 v[82:83], s[90:91], 0, v[220:221]
	global_store_dwordx4 v[82:83], v[86:89], off
	v_lshlrev_b32_e32 v84, 16, v88
	v_and_b32_e32 v85, 0xffff0000, v88
	v_lshlrev_b32_e32 v82, 16, v89
	v_and_b32_e32 v83, 0xffff0000, v89
	v_lshlrev_b32_e32 v88, 16, v86
	v_and_b32_e32 v89, 0xffff0000, v86
	v_lshlrev_b32_e32 v86, 16, v87
	v_and_b32_e32 v87, 0xffff0000, v87
	s_mov_b64 s[4:5], 0x58000
	s_waitcnt vmcnt(2)
; __device__ __forceinline__ unsigned cvt_pk_bf16(float lo, float hi) { unsigned r; asm volatile("v_cvt_pk_bf16_f32 %0, %1, %2" : "=v"(r) : "v"(lo), "v"(hi)); return r; }
;     __device__ __forceinline__ void operator()(const f32x4 (&acc)[2][2][4][2], const Unit& u, int wr, int wc, int fr, int fq) const {
;     ...
;                 for (int m = 0; m < 4; ++m) { const size_t off = (size_t)(row0 + ai * HALF + m * 16) * 2048 + col0 + bj * HALF;
;                     f32x4 x0 = __builtin_nontemporal_load((const f32x4*)(base + off)), x1 = __builtin_nontemporal_load((const f32x4*)(base + off + 4));
;                     if constexpr (HAS_DIN) { const u32x4 dw = __builtin_nontemporal_load((const u32x4*)(dbuf + off));
;                         x0 += (f32x4){__builtin_bit_cast(float, dw.x << 16), __builtin_bit_cast(float, dw.x & 0xffff0000u), __builtin_bit_cast(float, dw.y << 16), __builtin_bit_cast(float, dw.y & 0xffff0000u)};
;                         x1 += (f32x4){__builtin_bit_cast(float, dw.z << 16), __builtin_bit_cast(float, dw.z & 0xffff0000u), __builtin_bit_cast(float, dw.w << 16), __builtin_bit_cast(float, dw.w & 0xffff0000u)}; }
;                     f32x4 o0, o1;
;                     if constexpr (OUT_DELTA) { const f32x4 d0 = g0 * acc[ai][bj][m][0], d1 = g1 * acc[ai][bj][m][1];
;                         u32x4 w; w.x = cvt_pk_bf16(d0[0], d0[1]); w.y = cvt_pk_bf16(d0[2], d0[3]); w.z = cvt_pk_bf16(d1[0], d1[1]); w.w = cvt_pk_bf16(d1[2], d1[3]);
;                         *(u32x4*)(dbuf + off) = w;
;                         o0 = x0 + (f32x4){__builtin_bit_cast(float, w.x << 16), __builtin_bit_cast(float, w.x & 0xffff0000u), __builtin_bit_cast(float, w.y << 16), __builtin_bit_cast(float, w.y & 0xffff0000u)};
;                         o1 = x1 + (f32x4){__builtin_bit_cast(float, w.z << 16), __builtin_bit_cast(float, w.z & 0xffff0000u), __builtin_bit_cast(float, w.w << 16), __builtin_bit_cast(float, w.w & 0xffff0000u)}; }
;                     else { o0 = x0 + g0 * acc[ai][bj][m][0]; o1 = x1 + g1 * acc[ai][bj][m][1]; *(f32x4*)(out + off) = o0; *(f32x4*)(out + off + 4) = o1; }
;                     if (Hn) { const f32x4 h0 = o0 * G0, h1 = o1 * G1;
;                         u32x4 w; w.x = cvt_pk_bf16(h0[0], h0[1]); w.y = cvt_pk_bf16(h0[2], h0[3]); w.z = cvt_pk_bf16(h1[0], h1[1]); w.w = cvt_pk_bf16(h1[2], h1[3]);
;                         *(u32x4*)(Hn + off) = w;
	v_pk_add_f32 v[86:87], v[196:197], v[86:87]
	s_waitcnt vmcnt(1)
	v_pk_add_f32 v[82:83], v[214:215], v[82:83]
	v_pk_add_f32 v[88:89], v[194:195], v[88:89]
	v_pk_add_f32 v[84:85], v[212:213], v[84:85]
	v_pk_mul_f32 v[196:197], v[198:199], v[86:87]
	v_pk_mul_f32 v[194:195], v[200:201], v[88:89]
	v_pk_mul_f32 v[212:213], v[202:203], v[82:83]
	v_pk_mul_f32 v[214:215], v[204:205], v[84:85]
	v_cvt_pk_bf16_f32 v194, v194, v195
	v_cvt_pk_bf16_f32 v195, v196, v197
	s_nop 0
	v_cvt_pk_bf16_f32 v196, v214, v215
	v_cvt_pk_bf16_f32 v197, v212, v213
	v_lshl_add_u64 v[212:213], s[96:97], 0, v[220:221]
	global_store_dwordx4 v[212:213], v[194:197], off
	s_nop 1
	v_lshl_add_u64 v[196:197], v[184:185], 0, s[4:5]
	v_lshl_add_u64 v[224:225], v[196:197], 0, v[148:149]
	v_lshl_add_u64 v[194:195], v[224:225], 2, s[44:45]
	global_load_dwordx4 v[212:215], v[194:195], off nt
	global_load_dwordx4 v[220:223], v[194:195], off offset:16 nt
	v_lshlrev_b64 v[102:103], 1, v[224:225]
	v_cvt_pk_bf16_f32 v78, v78, v79
	v_cvt_pk_bf16_f32 v79, v80, v81
	v_cvt_pk_bf16_f32 v80, v74, v75
	v_cvt_pk_bf16_f32 v81, v76, v77
	v_lshl_add_u64 v[74:75], s[90:91], 0, v[102:103]
	global_store_dwordx4 v[74:75], v[78:81], off
	v_lshlrev_b32_e32 v76, 16, v80
	v_and_b32_e32 v77, 0xffff0000, v80
	v_lshlrev_b32_e32 v74, 16, v81
	v_and_b32_e32 v75, 0xffff0000, v81
	v_lshlrev_b32_e32 v80, 16, v78
	v_and_b32_e32 v81, 0xffff0000, v78
	v_lshlrev_b32_e32 v78, 16, v79
	v_and_b32_e32 v79, 0xffff0000, v79
	v_lshl_add_u64 v[102:103], s[96:97], 0, v[102:103]
	v_or_b32_e32 v148, 0x80, v148
	s_waitcnt vmcnt(2)
	v_pk_add_f32 v[78:79], v[214:215], v[78:79]
	v_pk_add_f32 v[80:81], v[212:213], v[80:81]
	s_waitcnt vmcnt(1)
	v_pk_add_f32 v[74:75], v[222:223], v[74:75]
	v_pk_add_f32 v[76:77], v[220:221], v[76:77]
	v_pk_mul_f32 v[100:101], v[198:199], v[78:79]
	v_pk_mul_f32 v[98:99], v[200:201], v[80:81]
	v_pk_mul_f32 v[104:105], v[202:203], v[74:75]
	v_pk_mul_f32 v[198:199], v[204:205], v[76:77]
	v_cvt_pk_bf16_f32 v98, v98, v99
	v_cvt_pk_bf16_f32 v99, v100, v101
	s_nop 0
	v_cvt_pk_bf16_f32 v100, v198, v199
	v_cvt_pk_bf16_f32 v101, v104, v105
	global_store_dwordx4 v[102:103], v[98:101], off
	global_load_dwordx4 v[100:103], v[178:179], off offset:512 nt
	global_load_dwordx4 v[198:201], v[178:179], off offset:528 nt
	v_lshl_add_u64 v[98:99], v[184:185], 0, v[148:149]
	v_pk_mul_f32 v[104:105], v[68:69], v[28:29]
	v_pk_mul_f32 v[68:69], v[66:67], v[26:27]
	v_cvt_pk_bf16_f32 v66, v70, v71
	v_cvt_pk_bf16_f32 v67, v72, v73
	s_nop 0
	v_cvt_pk_bf16_f32 v68, v68, v69
	v_cvt_pk_bf16_f32 v69, v104, v105
	v_lshlrev_b64 v[104:105], 1, v[98:99]
	v_lshl_add_u64 v[70:71], s[90:91], 0, v[104:105]
	global_store_dwordx4 v[70:71], v[66:69], off
	v_lshlrev_b32_e32 v72, 16, v68
	v_and_b32_e32 v73, 0xffff0000, v68
	v_lshlrev_b32_e32 v68, 16, v69
	v_and_b32_e32 v69, 0xffff0000, v69
	s_waitcnt vmcnt(1)
	v_pk_add_f32 v[70:71], v[200:201], v[68:69]
	v_lshlrev_b32_e32 v68, 16, v66
	v_and_b32_e32 v69, 0xffff0000, v66
	v_lshlrev_b32_e32 v66, 16, v67
	v_and_b32_e32 v67, 0xffff0000, v67
	v_pk_add_f32 v[98:99], v[102:103], v[66:67]
	v_pk_add_f32 v[100:101], v[100:101], v[68:69]
	v_pk_add_f32 v[72:73], v[198:199], v[72:73]
	v_pk_mul_f32 v[68:69], v[150:151], v[98:99]
	v_pk_mul_f32 v[66:67], v[152:153], v[100:101]
	v_pk_mul_f32 v[102:103], v[154:155], v[70:71]
	v_pk_mul_f32 v[178:179], v[156:157], v[72:73]
	v_cvt_pk_bf16_f32 v66, v66, v67
	v_cvt_pk_bf16_f32 v67, v68, v69
	s_nop 0
	v_cvt_pk_bf16_f32 v68, v178, v179
	v_cvt_pk_bf16_f32 v69, v102, v103
	v_lshl_add_u64 v[102:103], s[96:97], 0, v[104:105]
	global_store_dwordx4 v[102:103], v[66:69], off
	s_nop 1
	v_mul_f32_e32 v66, v101, v101
	v_mul_f32_e32 v67, v99, v99
	v_fmac_f32_e32 v66, v100, v100
	v_fmac_f32_e32 v67, v98, v98
	v_add_f32_e32 v66, v66, v67
	v_mul_f32_e32 v67, v73, v73
	v_mul_f32_e32 v68, v71, v71
	v_fmac_f32_e32 v67, v72, v72
	v_fmac_f32_e32 v68, v70, v70
	v_add_f32_e32 v67, v67, v68
	global_load_dwordx4 v[68:71], v[138:139], off offset:512 nt
	global_load_dwordx4 v[98:101], v[138:139], off offset:528 nt
	v_lshl_add_u64 v[72:73], v[140:141], 0, v[148:149]
	v_lshlrev_b64 v[72:73], 1, v[72:73]
	v_cvt_pk_bf16_f32 v62, v62, v63
	v_cvt_pk_bf16_f32 v63, v64, v65
	v_cvt_pk_bf16_f32 v64, v58, v59
	v_cvt_pk_bf16_f32 v65, v60, v61
	v_lshl_add_u64 v[58:59], s[90:91], 0, v[72:73]
	global_store_dwordx4 v[58:59], v[62:65], off
	v_lshlrev_b32_e32 v60, 16, v64
	v_and_b32_e32 v61, 0xffff0000, v64
	v_lshlrev_b32_e32 v58, 16, v65
	v_and_b32_e32 v59, 0xffff0000, v65
	v_lshlrev_b32_e32 v64, 16, v62
	v_and_b32_e32 v65, 0xffff0000, v62
	v_lshlrev_b32_e32 v62, 16, v63
	v_and_b32_e32 v63, 0xffff0000, v63
	v_lshl_add_u64 v[72:73], s[96:97], 0, v[72:73]
	v_add_f32_e32 v66, v66, v67
	v_add_f32_e32 v66, v211, v66
	s_waitcnt vmcnt(2)
	v_pk_add_f32 v[62:63], v[70:71], v[62:63]
	v_pk_add_f32 v[64:65], v[68:69], v[64:65]
	s_waitcnt vmcnt(1)
	v_pk_add_f32 v[58:59], v[100:101], v[58:59]
	v_pk_add_f32 v[60:61], v[98:99], v[60:61]
	v_pk_mul_f32 v[70:71], v[150:151], v[62:63]
	v_pk_mul_f32 v[68:69], v[152:153], v[64:65]
	v_pk_mul_f32 v[98:99], v[154:155], v[58:59]
	v_pk_mul_f32 v[100:101], v[156:157], v[60:61]
	v_cvt_pk_bf16_f32 v68, v68, v69
	v_cvt_pk_bf16_f32 v69, v70, v71
	s_nop 0
	v_cvt_pk_bf16_f32 v70, v100, v101
	v_cvt_pk_bf16_f32 v71, v98, v99
	global_store_dwordx4 v[72:73], v[68:71], off
	global_load_dwordx4 v[68:71], v[142:143], off offset:512 nt
	s_nop 0
	global_load_dwordx4 v[98:101], v[142:143], off offset:528 nt
	v_lshl_add_u64 v[72:73], v[144:145], 0, v[148:149]
	v_lshlrev_b64 v[72:73], 1, v[72:73]
	v_cvt_pk_bf16_f32 v54, v54, v55
	v_cvt_pk_bf16_f32 v55, v56, v57
	v_cvt_pk_bf16_f32 v56, v50, v51
	v_cvt_pk_bf16_f32 v57, v52, v53
	v_lshl_add_u64 v[50:51], s[90:91], 0, v[72:73]
	global_store_dwordx4 v[50:51], v[54:57], off
	v_lshlrev_b32_e32 v52, 16, v56
	v_and_b32_e32 v53, 0xffff0000, v56
	v_lshlrev_b32_e32 v50, 16, v57
	v_and_b32_e32 v51, 0xffff0000, v57
	v_lshlrev_b32_e32 v56, 16, v54
	v_and_b32_e32 v57, 0xffff0000, v54
	v_lshlrev_b32_e32 v54, 16, v55
	v_and_b32_e32 v55, 0xffff0000, v55
	v_lshl_add_u64 v[72:73], s[96:97], 0, v[72:73]
	s_waitcnt vmcnt(2)
; __device__ __forceinline__ unsigned cvt_pk_bf16(float lo, float hi) { unsigned r; asm volatile("v_cvt_pk_bf16_f32 %0, %1, %2" : "=v"(r) : "v"(lo), "v"(hi)); return r; }
;     __device__ __forceinline__ void operator()(const f32x4 (&acc)[2][2][4][2], const Unit& u, int wr, int wc, int fr, int fq) const {
;     ...
;                 for (int m = 0; m < 4; ++m) { const size_t off = (size_t)(row0 + ai * HALF + m * 16) * 2048 + col0 + bj * HALF;
;                     f32x4 x0 = __builtin_nontemporal_load((const f32x4*)(base + off)), x1 = __builtin_nontemporal_load((const f32x4*)(base + off + 4));
;                     if constexpr (HAS_DIN) { const u32x4 dw = __builtin_nontemporal_load((const u32x4*)(dbuf + off));
;                         x0 += (f32x4){__builtin_bit_cast(float, dw.x << 16), __builtin_bit_cast(float, dw.x & 0xffff0000u), __builtin_bit_cast(float, dw.y << 16), __builtin_bit_cast(float, dw.y & 0xffff0000u)};
;                         x1 += (f32x4){__builtin_bit_cast(float, dw.z << 16), __builtin_bit_cast(float, dw.z & 0xffff0000u), __builtin_bit_cast(float, dw.w << 16), __builtin_bit_cast(float, dw.w & 0xffff0000u)}; }
;                     f32x4 o0, o1;
;                     if constexpr (OUT_DELTA) { const f32x4 d0 = g0 * acc[ai][bj][m][0], d1 = g1 * acc[ai][bj][m][1];
;                         u32x4 w; w.x = cvt_pk_bf16(d0[0], d0[1]); w.y = cvt_pk_bf16(d0[2], d0[3]); w.z = cvt_pk_bf16(d1[0], d1[1]); w.w = cvt_pk_bf16(d1[2], d1[3]);
;                         *(u32x4*)(dbuf + off) = w;
;                         o0 = x0 + (f32x4){__builtin_bit_cast(float, w.x << 16), __builtin_bit_cast(float, w.x & 0xffff0000u), __builtin_bit_cast(float, w.y << 16), __builtin_bit_cast(float, w.y & 0xffff0000u)};
;                         o1 = x1 + (f32x4){__builtin_bit_cast(float, w.z << 16), __builtin_bit_cast(float, w.z & 0xffff0000u), __builtin_bit_cast(float, w.w << 16), __builtin_bit_cast(float, w.w & 0xffff0000u)}; }
;                     else { o0 = x0 + g0 * acc[ai][bj][m][0]; o1 = x1 + g1 * acc[ai][bj][m][1]; *(f32x4*)(out + off) = o0; *(f32x4*)(out + off + 4) = o1; }
;                     if (Hn) { const f32x4 h0 = o0 * G0, h1 = o1 * G1;
;                         u32x4 w; w.x = cvt_pk_bf16(h0[0], h0[1]); w.y = cvt_pk_bf16(h0[2], h0[3]); w.z = cvt_pk_bf16(h1[0], h1[1]); w.w = cvt_pk_bf16(h1[2], h1[3]);
;                         *(u32x4*)(Hn + off) = w;
	v_pk_add_f32 v[54:55], v[70:71], v[54:55]
	v_pk_add_f32 v[56:57], v[68:69], v[56:57]
	s_waitcnt vmcnt(1)
	v_pk_add_f32 v[50:51], v[100:101], v[50:51]
	v_pk_add_f32 v[52:53], v[98:99], v[52:53]
	v_pk_mul_f32 v[70:71], v[150:151], v[54:55]
	v_pk_mul_f32 v[68:69], v[152:153], v[56:57]
	v_pk_mul_f32 v[98:99], v[154:155], v[50:51]
	v_pk_mul_f32 v[100:101], v[156:157], v[52:53]
	v_cvt_pk_bf16_f32 v68, v68, v69
	v_cvt_pk_bf16_f32 v69, v70, v71
	s_nop 0
	v_cvt_pk_bf16_f32 v70, v100, v101
	v_cvt_pk_bf16_f32 v71, v98, v99
	global_store_dwordx4 v[72:73], v[68:71], off
	global_load_dwordx4 v[68:71], v[158:159], off offset:512 nt
	s_nop 0
	global_load_dwordx4 v[98:101], v[158:159], off offset:528 nt
	v_lshl_add_u64 v[72:73], v[160:161], 0, v[148:149]
	v_lshlrev_b64 v[72:73], 1, v[72:73]
	v_cvt_pk_bf16_f32 v46, v46, v47
	v_cvt_pk_bf16_f32 v47, v48, v49
	v_cvt_pk_bf16_f32 v48, v42, v43
	v_cvt_pk_bf16_f32 v49, v44, v45
	v_lshl_add_u64 v[42:43], s[90:91], 0, v[72:73]
	global_store_dwordx4 v[42:43], v[46:49], off
	v_lshlrev_b32_e32 v44, 16, v48
	v_and_b32_e32 v45, 0xffff0000, v48
	v_lshlrev_b32_e32 v42, 16, v49
	v_and_b32_e32 v43, 0xffff0000, v49
	v_lshlrev_b32_e32 v48, 16, v46
	v_and_b32_e32 v49, 0xffff0000, v46
	v_lshlrev_b32_e32 v46, 16, v47
	v_and_b32_e32 v47, 0xffff0000, v47
	v_lshl_add_u64 v[72:73], s[96:97], 0, v[72:73]
	s_waitcnt vmcnt(2)
	v_pk_add_f32 v[46:47], v[70:71], v[46:47]
	v_pk_add_f32 v[48:49], v[68:69], v[48:49]
	s_waitcnt vmcnt(1)
	v_pk_add_f32 v[42:43], v[100:101], v[42:43]
	v_pk_add_f32 v[44:45], v[98:99], v[44:45]
	v_pk_mul_f32 v[70:71], v[150:151], v[46:47]
	v_pk_mul_f32 v[68:69], v[152:153], v[48:49]
	v_pk_mul_f32 v[98:99], v[154:155], v[42:43]
	v_pk_mul_f32 v[100:101], v[156:157], v[44:45]
	v_cvt_pk_bf16_f32 v68, v68, v69
	v_cvt_pk_bf16_f32 v69, v70, v71
	s_nop 0
	v_cvt_pk_bf16_f32 v70, v100, v101
	v_cvt_pk_bf16_f32 v71, v98, v99
	global_store_dwordx4 v[72:73], v[68:71], off
	global_load_dwordx4 v[68:71], v[180:181], off offset:512 nt
	s_nop 0
	global_load_dwordx4 v[98:101], v[180:181], off offset:528 nt
	v_lshl_add_u64 v[72:73], v[182:183], 0, v[148:149]
	v_lshlrev_b64 v[72:73], 1, v[72:73]
	v_cvt_pk_bf16_f32 v38, v38, v39
	v_cvt_pk_bf16_f32 v39, v40, v41
	v_cvt_pk_bf16_f32 v40, v34, v35
	v_cvt_pk_bf16_f32 v41, v36, v37
	v_lshl_add_u64 v[34:35], s[90:91], 0, v[72:73]
	global_store_dwordx4 v[34:35], v[38:41], off
	v_lshlrev_b32_e32 v36, 16, v40
	v_and_b32_e32 v37, 0xffff0000, v40
	v_lshlrev_b32_e32 v34, 16, v41
	v_and_b32_e32 v35, 0xffff0000, v41
	v_lshlrev_b32_e32 v40, 16, v38
	v_and_b32_e32 v41, 0xffff0000, v38
	v_lshlrev_b32_e32 v38, 16, v39
	v_and_b32_e32 v39, 0xffff0000, v39
	v_lshl_add_u64 v[72:73], s[96:97], 0, v[72:73]
	s_waitcnt vmcnt(2)
	v_pk_add_f32 v[38:39], v[70:71], v[38:39]
	v_pk_add_f32 v[40:41], v[68:69], v[40:41]
	s_waitcnt vmcnt(1)
	v_pk_add_f32 v[34:35], v[100:101], v[34:35]
	v_pk_add_f32 v[36:37], v[98:99], v[36:37]
	v_pk_mul_f32 v[70:71], v[150:151], v[38:39]
	v_pk_mul_f32 v[68:69], v[152:153], v[40:41]
	v_pk_mul_f32 v[98:99], v[154:155], v[34:35]
	v_pk_mul_f32 v[100:101], v[156:157], v[36:37]
	v_cvt_pk_bf16_f32 v68, v68, v69
	v_cvt_pk_bf16_f32 v69, v70, v71
	s_nop 0
	v_cvt_pk_bf16_f32 v70, v100, v101
	v_cvt_pk_bf16_f32 v71, v98, v99
	global_store_dwordx4 v[72:73], v[68:71], off
	global_load_dwordx4 v[68:71], v[186:187], off offset:512 nt
	s_nop 0
	global_load_dwordx4 v[98:101], v[186:187], off offset:528 nt
	v_lshl_add_u64 v[72:73], v[188:189], 0, v[148:149]
	v_lshlrev_b64 v[72:73], 1, v[72:73]
	v_cvt_pk_bf16_f32 v22, v22, v23
	v_cvt_pk_bf16_f32 v23, v24, v25
	v_cvt_pk_bf16_f32 v24, v18, v19
	v_cvt_pk_bf16_f32 v25, v20, v21
	v_lshl_add_u64 v[18:19], s[90:91], 0, v[72:73]
	global_store_dwordx4 v[18:19], v[22:25], off
	v_lshlrev_b32_e32 v20, 16, v24
	v_and_b32_e32 v21, 0xffff0000, v24
	v_lshlrev_b32_e32 v18, 16, v25
	v_and_b32_e32 v19, 0xffff0000, v25
	v_lshlrev_b32_e32 v24, 16, v22
	v_and_b32_e32 v25, 0xffff0000, v22
	v_lshlrev_b32_e32 v22, 16, v23
	v_and_b32_e32 v23, 0xffff0000, v23
	v_lshl_add_u64 v[72:73], s[96:97], 0, v[72:73]
	s_waitcnt vmcnt(2)
	v_pk_add_f32 v[22:23], v[70:71], v[22:23]
	v_pk_add_f32 v[24:25], v[68:69], v[24:25]
	s_waitcnt vmcnt(1)
; __device__ __forceinline__ unsigned cvt_pk_bf16(float lo, float hi) { unsigned r; asm volatile("v_cvt_pk_bf16_f32 %0, %1, %2" : "=v"(r) : "v"(lo), "v"(hi)); return r; }
;     __device__ __forceinline__ void operator()(const f32x4 (&acc)[2][2][4][2], const Unit& u, int wr, int wc, int fr, int fq) const {
;     ...
;                 for (int m = 0; m < 4; ++m) { const size_t off = (size_t)(row0 + ai * HALF + m * 16) * 2048 + col0 + bj * HALF;
;                     f32x4 x0 = __builtin_nontemporal_load((const f32x4*)(base + off)), x1 = __builtin_nontemporal_load((const f32x4*)(base + off + 4));
;                     if constexpr (HAS_DIN) { const u32x4 dw = __builtin_nontemporal_load((const u32x4*)(dbuf + off));
;                         x0 += (f32x4){__builtin_bit_cast(float, dw.x << 16), __builtin_bit_cast(float, dw.x & 0xffff0000u), __builtin_bit_cast(float, dw.y << 16), __builtin_bit_cast(float, dw.y & 0xffff0000u)};
;                         x1 += (f32x4){__builtin_bit_cast(float, dw.z << 16), __builtin_bit_cast(float, dw.z & 0xffff0000u), __builtin_bit_cast(float, dw.w << 16), __builtin_bit_cast(float, dw.w & 0xffff0000u)}; }
;                     f32x4 o0, o1;
;                     if constexpr (OUT_DELTA) { const f32x4 d0 = g0 * acc[ai][bj][m][0], d1 = g1 * acc[ai][bj][m][1];
;                         u32x4 w; w.x = cvt_pk_bf16(d0[0], d0[1]); w.y = cvt_pk_bf16(d0[2], d0[3]); w.z = cvt_pk_bf16(d1[0], d1[1]); w.w = cvt_pk_bf16(d1[2], d1[3]);
;                         *(u32x4*)(dbuf + off) = w;
;                         o0 = x0 + (f32x4){__builtin_bit_cast(float, w.x << 16), __builtin_bit_cast(float, w.x & 0xffff0000u), __builtin_bit_cast(float, w.y << 16), __builtin_bit_cast(float, w.y & 0xffff0000u)};
;                         o1 = x1 + (f32x4){__builtin_bit_cast(float, w.z << 16), __builtin_bit_cast(float, w.z & 0xffff0000u), __builtin_bit_cast(float, w.w << 16), __builtin_bit_cast(float, w.w & 0xffff0000u)}; }
;                     else { o0 = x0 + g0 * acc[ai][bj][m][0]; o1 = x1 + g1 * acc[ai][bj][m][1]; *(f32x4*)(out + off) = o0; *(f32x4*)(out + off + 4) = o1; }
;                     if (Hn) { const f32x4 h0 = o0 * G0, h1 = o1 * G1;
;                         u32x4 w; w.x = cvt_pk_bf16(h0[0], h0[1]); w.y = cvt_pk_bf16(h0[2], h0[3]); w.z = cvt_pk_bf16(h1[0], h1[1]); w.w = cvt_pk_bf16(h1[2], h1[3]);
;                         *(u32x4*)(Hn + off) = w;
	v_pk_add_f32 v[18:19], v[100:101], v[18:19]
	v_pk_add_f32 v[20:21], v[98:99], v[20:21]
	v_pk_mul_f32 v[70:71], v[150:151], v[22:23]
	v_pk_mul_f32 v[68:69], v[152:153], v[24:25]
	v_pk_mul_f32 v[98:99], v[154:155], v[18:19]
	v_pk_mul_f32 v[100:101], v[156:157], v[20:21]
	v_cvt_pk_bf16_f32 v68, v68, v69
	v_cvt_pk_bf16_f32 v69, v70, v71
	s_nop 0
	v_cvt_pk_bf16_f32 v70, v100, v101
	v_cvt_pk_bf16_f32 v71, v98, v99
	global_store_dwordx4 v[72:73], v[68:71], off
	global_load_dwordx4 v[68:71], v[190:191], off offset:512 nt
	s_nop 0
	global_load_dwordx4 v[98:101], v[190:191], off offset:528 nt
	v_lshl_add_u64 v[72:73], v[192:193], 0, v[148:149]
	v_lshlrev_b64 v[72:73], 1, v[72:73]
	v_cvt_pk_bf16_f32 v14, v14, v15
	v_cvt_pk_bf16_f32 v15, v16, v17
	v_cvt_pk_bf16_f32 v16, v10, v11
	v_cvt_pk_bf16_f32 v17, v12, v13
	v_lshl_add_u64 v[10:11], s[90:91], 0, v[72:73]
	global_store_dwordx4 v[10:11], v[14:17], off
	v_lshlrev_b32_e32 v12, 16, v16
	v_and_b32_e32 v13, 0xffff0000, v16
	v_lshlrev_b32_e32 v10, 16, v17
	v_and_b32_e32 v11, 0xffff0000, v17
	v_lshlrev_b32_e32 v16, 16, v14
	v_and_b32_e32 v17, 0xffff0000, v14
	v_lshlrev_b32_e32 v14, 16, v15
	v_and_b32_e32 v15, 0xffff0000, v15
	v_lshl_add_u64 v[72:73], s[96:97], 0, v[72:73]
	s_waitcnt vmcnt(2)
	v_pk_add_f32 v[14:15], v[70:71], v[14:15]
	v_pk_add_f32 v[16:17], v[68:69], v[16:17]
	s_waitcnt vmcnt(1)
	v_pk_add_f32 v[10:11], v[100:101], v[10:11]
	v_pk_add_f32 v[12:13], v[98:99], v[12:13]
	v_pk_mul_f32 v[70:71], v[150:151], v[14:15]
	v_pk_mul_f32 v[68:69], v[152:153], v[16:17]
	v_pk_mul_f32 v[98:99], v[154:155], v[10:11]
	v_pk_mul_f32 v[100:101], v[156:157], v[12:13]
	v_cvt_pk_bf16_f32 v68, v68, v69
	v_cvt_pk_bf16_f32 v69, v70, v71
	s_nop 0
	v_cvt_pk_bf16_f32 v70, v100, v101
	v_cvt_pk_bf16_f32 v71, v98, v99
	global_store_dwordx4 v[72:73], v[68:71], off
	global_load_dwordx4 v[68:71], v[194:195], off offset:512 nt
	s_nop 0
	global_load_dwordx4 v[98:101], v[194:195], off offset:528 nt
	v_lshl_add_u64 v[72:73], v[196:197], 0, v[148:149]
	v_lshlrev_b64 v[30:31], 1, v[72:73]
	v_cvt_pk_bf16_f32 v6, v6, v7
	v_cvt_pk_bf16_f32 v7, v8, v9
	v_cvt_pk_bf16_f32 v8, v2, v3
	v_cvt_pk_bf16_f32 v9, v4, v5
	v_lshl_add_u64 v[2:3], s[90:91], 0, v[30:31]
	global_store_dwordx4 v[2:3], v[6:9], off
	v_lshlrev_b32_e32 v4, 16, v8
	v_and_b32_e32 v5, 0xffff0000, v8
	v_lshlrev_b32_e32 v2, 16, v9
	v_and_b32_e32 v3, 0xffff0000, v9
	v_lshlrev_b32_e32 v8, 16, v6
	v_and_b32_e32 v9, 0xffff0000, v6
	v_lshlrev_b32_e32 v6, 16, v7
	v_and_b32_e32 v7, 0xffff0000, v7
	v_lshl_add_u64 v[30:31], s[96:97], 0, v[30:31]
	s_waitcnt vmcnt(2)
	v_pk_add_f32 v[8:9], v[68:69], v[8:9]
	v_pk_add_f32 v[6:7], v[70:71], v[6:7]
	v_pk_mul_f32 v[26:27], v[152:153], v[8:9]
	s_waitcnt vmcnt(1)
	v_pk_add_f32 v[2:3], v[100:101], v[2:3]
	v_pk_add_f32 v[4:5], v[98:99], v[4:5]
	v_pk_mul_f32 v[28:29], v[150:151], v[6:7]
	v_cvt_pk_bf16_f32 v26, v26, v27
	v_pk_mul_f32 v[32:33], v[154:155], v[2:3]
	v_cvt_pk_bf16_f32 v27, v28, v29
	v_pk_mul_f32 v[68:69], v[156:157], v[4:5]
	s_nop 0
	v_cvt_pk_bf16_f32 v28, v68, v69
	v_cvt_pk_bf16_f32 v29, v32, v33
	global_store_dwordx4 v[30:31], v[26:29], off
	s_nop 1
	v_and_b32_e32 v27, 64, v218
	v_xor_b32_e32 v26, 16, v218
	v_add_u32_e32 v27, 64, v27
	v_cmp_lt_i32_e32 vcc, v26, v27
	s_nop 1
	v_cndmask_b32_e32 v26, v218, v26, vcc
	v_lshlrev_b32_e32 v28, 2, v26
	v_xor_b32_e32 v26, 32, v218
	v_cmp_lt_i32_e32 vcc, v26, v27
	s_nop 1
	v_cndmask_b32_e32 v26, v218, v26, vcc
	v_lshlrev_b32_e32 v29, 2, v26
	ds_bpermute_b32 v26, v28, v66
	s_waitcnt lgkmcnt(0)
	v_add_f32_e32 v30, v66, v26
	ds_bpermute_b32 v31, v29, v30
	v_lshl_add_u64 v[26:27], v[146:147], 3, s[42:43]
	s_and_saveexec_b64 s[4:5], s[0:1]
	s_mov_b32 s8, 0x2f800000
	s_mov_b32 s9, 0xcf800000
	s_cbranch_execz .LBB0_558
	s_waitcnt lgkmcnt(0)
	v_add_f32_e32 v30, v30, v31
	v_mul_f32_e32 v30, 0x47800000, v30
	v_rndne_f32_e32 v30, v30
	v_mul_f32_e64 v31, |v30|, s8
	v_floor_f32_e32 v31, v31
	v_fma_f32 v32, v31, s9, |v30|
	v_cvt_u32_f32_e32 v32, v32
	v_cvt_u32_f32_e32 v31, v31
	v_ashrrev_i32_e32 v33, 31, v30
	v_xor_b32_e32 v30, v32, v33
	v_xor_b32_e32 v31, v31, v33
	v_sub_co_u32_e32 v30, vcc, v30, v33
	s_nop 1
	v_subb_co_u32_e32 v31, vcc, v31, v33, vcc
	global_atomic_add_x2 v[26:27], v[30:31], off

; #define PG8_STAGE(bufoff, gbase, voff) do { const char* gb_ = (const char*)(gbase); asm volatile("" : "+s"(gb_)); _Pragma("unroll") for (int _i = 0; _i < 2; ++_i) { unsigned vo_ = (voff)[_i]; asm volatile("" : "+v"(vo_));        \
;         __builtin_amdgcn_global_load_lds((const unsigned*)(gb_ + vo_), (PG8_LAS unsigned*)(lds + (bufoff) + ldsw + _i * 8192), 16, 0, 0); } } while (0)
; #define PG8_LDA(dst, b, h) do { _Pragma("unroll") for (int m = 0; m < 4; ++m) _Pragma("unroll") for (int k = 0; k < 2; ++k) dst[m][k] = *(const PG8_LAS bf16x8*)(lds + PG8_SA(b, h) + aoff + m * 2048 + k * 1024); } while (0)
; #define PG8_WAIT_V(n) asm volatile("s_waitcnt vmcnt(" #n ")" ::: "memory")
; #define PG8_WAIT_L(n) asm volatile("s_waitcnt lgkmcnt(" #n ")" ::: "memory")
; template <class Epi, class Sched, bool ALIGN_EPI = false, bool SP2 = false>
; __device__ __forceinline__ void gemm_phase(PG8_LAS unsigned char* lds, const Gemm g, const Sched& S, const Epi& E) {
;     ...
;             const bool last = (t == nt - 2);
;             const char* a1 = cA + (size_t)(t + 1) * kstep;
;             const char* a2 = last ? nA : cA + (size_t)(t + 2) * kstep; const char* b2 = last ? nB : cB + (size_t)(t + 2) * kstep;
;             const char* a3 = a2 + kstep; const char* b3 = b2 + kstep;
;             if (last && has_next) S.a_ready(nxt);
;             if constexpr (SP2) {
;             PG8_LDB(B0, 0, 0); PG8_LDB(B1, 0, 1); PG8_SCHED; PG8_LDA(At, 0, 0); PG8_STAGE(PG8_SA(1, 1), a1 + hstep, voffA);
;             PG8_WAIT_V(8); PG8_WAIT_L(0); PG8_BAR; PG8_MMA(0, 0, At, B0); PG8_MMA(0, 1, At, B1); PG8_BAR; PG8_SCHED;
;             PG8_LDA(At, 0, 1); PG8_STAGE(PG8_SB(0, 0), b2, voffB); PG8_STAGE(PG8_SB(0, 1), b2 + hstep, voffB); PG8_STAGE(PG8_SA(0, 0), a2, voffA);
;             PG8_WAIT_V(8); PG8_WAIT_L(0); PG8_BAR; PG8_MMA(1, 0, At, B0); PG8_MMA(1, 1, At, B1); PG8_BAR; PG8_SCHED;
;             PG8_LDB(B0, 1, 0); PG8_LDB(B1, 1, 1); PG8_SCHED; PG8_LDA(At, 1, 0); PG8_STAGE(PG8_SA(0, 1), a2 + hstep, voffA);
;             PG8_WAIT_V(8); PG8_WAIT_L(0); PG8_BAR; PG8_MMA(0, 0, At, B0); PG8_MMA(0, 1, At, B1); PG8_BAR; PG8_SCHED;
;             PG8_LDA(At, 1, 1); PG8_STAGE(PG8_SB(1, 0), b3, voffB); PG8_STAGE(PG8_SB(1, 1), b3 + hstep, voffB); PG8_STAGE(PG8_SA(1, 0), a3, voffA);
;             PG8_WAIT_V(8); PG8_WAIT_L(0); PG8_BAR; PG8_MMA(1, 0, At, B0); PG8_MMA(1, 1, At, B1); PG8_BAR; PG8_SCHED;
.LBB0_634:
	s_add_u32 s16, s14, 0x100
	s_addc_u32 s17, s15, 0
	s_cmp_eq_u32 s53, 28
	s_cselect_b32 s22, s49, s16
	s_cselect_b32 s23, s7, s17
	s_cselect_b32 s20, s50, s51
	s_cselect_b32 s21, s5, s52
	s_add_u32 s18, s22, 0x80
	s_addc_u32 s19, s23, 0
	s_add_i32 s54, 0, 0x10000
	s_add_i32 s55, 0, 0x14000
	ds_read_b128 v[82:85], v244
	ds_read_b128 v[86:89], v244 offset:1024
	ds_read_b128 v[90:93], v244 offset:2048
	ds_read_b128 v[94:97], v244 offset:3072
	ds_read_b128 v[146:149], v244 offset:16384
	ds_read_b128 v[150:153], v244 offset:17408
	ds_read_b128 v[154:157], v244 offset:18432
	ds_read_b128 v[158:161], v244 offset:19456
	s_add_u32 s14, s14, 0x80080
	s_addc_u32 s15, s15, 0
	ds_read_b128 v[178:181], v188
	ds_read_b128 v[190:193], v188 offset:1024
	ds_read_b128 v[194:197], v188 offset:2048
	ds_read_b128 v[198:201], v188 offset:3072
	ds_read_b128 v[202:205], v188 offset:4096
	ds_read_b128 v[206:209], v188 offset:5120
	ds_read_b128 v[210:213], v188 offset:6144
	ds_read_b128 v[220:223], v188 offset:7168
	s_add_i32 m0, s27, 0xc000
	s_nop 0
	global_load_lds_dwordx4 v1, s[14:15]
	s_add_i32 m0, s27, 0xe000
	s_nop 0
	global_load_lds_dwordx4 v164, s[14:15]
	s_waitcnt vmcnt(8)
	s_waitcnt lgkmcnt(0)
	s_barrier
	s_setprio 1
	s_waitcnt lgkmcnt(0)
	v_mfma_f32_16x16x32_bf16 v[142:145], v[82:85], v[178:181], v[142:145]
	v_mfma_f32_16x16x32_bf16 v[142:145], v[86:89], v[190:193], v[142:145]
	v_mfma_f32_16x16x32_bf16 v[138:141], v[94:97], v[190:193], v[138:141]
	v_mfma_f32_16x16x32_bf16 v[138:141], v[90:93], v[178:181], v[138:141]
	v_mfma_f32_16x16x32_bf16 v[122:125], v[90:93], v[194:197], v[122:125]
	v_mfma_f32_16x16x32_bf16 v[122:125], v[94:97], v[198:201], v[122:125]
	v_mfma_f32_16x16x32_bf16 v[126:129], v[86:89], v[198:201], v[126:129]
	v_mfma_f32_16x16x32_bf16 v[126:129], v[82:85], v[194:197], v[126:129]
	v_mfma_f32_16x16x32_bf16 v[110:113], v[82:85], v[202:205], v[110:113]
	v_mfma_f32_16x16x32_bf16 v[110:113], v[86:89], v[206:209], v[110:113]
	v_mfma_f32_16x16x32_bf16 v[106:109], v[94:97], v[206:209], v[106:109]
	v_mfma_f32_16x16x32_bf16 v[106:109], v[90:93], v[202:205], v[106:109]
	v_mfma_f32_16x16x32_bf16 v[74:77], v[90:93], v[210:213], v[74:77]
	v_mfma_f32_16x16x32_bf16 v[74:77], v[94:97], v[220:223], v[74:77]
	v_mfma_f32_16x16x32_bf16 v[78:81], v[86:89], v[220:223], v[78:81]
	v_mfma_f32_16x16x32_bf16 v[78:81], v[82:85], v[210:213], v[78:81]
	s_setprio 0
	s_setprio 1
	v_mfma_f32_16x16x32_bf16 v[134:137], v[146:149], v[178:181], v[134:137]
	v_mfma_f32_16x16x32_bf16 v[134:137], v[150:153], v[190:193], v[134:137]
	v_mfma_f32_16x16x32_bf16 v[130:133], v[158:161], v[190:193], v[130:133]
	v_mfma_f32_16x16x32_bf16 v[130:133], v[154:157], v[178:181], v[130:133]
	v_mfma_f32_16x16x32_bf16 v[114:117], v[154:157], v[194:197], v[114:117]
	v_mfma_f32_16x16x32_bf16 v[114:117], v[158:161], v[198:201], v[114:117]
	v_mfma_f32_16x16x32_bf16 v[118:121], v[150:153], v[198:201], v[118:121]
	v_mfma_f32_16x16x32_bf16 v[118:121], v[146:149], v[194:197], v[118:121]
	v_mfma_f32_16x16x32_bf16 v[102:105], v[146:149], v[202:205], v[102:105]
	v_mfma_f32_16x16x32_bf16 v[102:105], v[150:153], v[206:209], v[102:105]
	v_mfma_f32_16x16x32_bf16 v[98:101], v[158:161], v[206:209], v[98:101]
	v_mfma_f32_16x16x32_bf16 v[98:101], v[154:157], v[202:205], v[98:101]
	v_mfma_f32_16x16x32_bf16 v[66:69], v[154:157], v[210:213], v[66:69]
	v_mfma_f32_16x16x32_bf16 v[66:69], v[158:161], v[220:223], v[66:69]
	v_mfma_f32_16x16x32_bf16 v[70:73], v[150:153], v[220:223], v[70:73]
	v_mfma_f32_16x16x32_bf16 v[70:73], v[146:149], v[210:213], v[70:73]
	s_setprio 0
	s_barrier
	s_mov_b64 s[14:15], s[20:21]
	s_add_i32 s54, s54, s26
	ds_read_b128 v[178:181], v188 offset:16384
	ds_read_b128 v[190:193], v188 offset:17408
	ds_read_b128 v[194:197], v188 offset:18432
	ds_read_b128 v[198:201], v188 offset:19456
	ds_read_b128 v[202:205], v188 offset:20480
	ds_read_b128 v[206:209], v188 offset:21504
	ds_read_b128 v[210:213], v188 offset:22528
	ds_read_b128 v[220:223], v188 offset:23552
	s_mov_b32 m0, s54
	s_nop 0
	global_load_lds_dwordx4 v162, s[14:15]
	s_add_i32 m0, s54, 0x2000
	s_nop 0
	global_load_lds_dwordx4 v184, s[14:15]
	s_add_u32 s14, s20, 0x80000
	s_addc_u32 s15, s21, 0
	s_add_i32 s54, s55, s26
	s_mov_b32 m0, s54
	s_nop 0
	global_load_lds_dwordx4 v162, s[14:15]
	s_add_i32 m0, s54, 0x2000
	s_nop 0
	global_load_lds_dwordx4 v184, s[14:15]
	s_mov_b64 s[14:15], s[22:23]
	s_mov_b32 m0, s27
	s_nop 0
	global_load_lds_dwordx4 v1, s[14:15]
	s_mov_b32 m0, s28
	s_nop 0
	global_load_lds_dwordx4 v164, s[14:15]
	s_waitcnt vmcnt(8)
	s_waitcnt lgkmcnt(0)
	s_barrier
; #define PG8_STAGE(bufoff, gbase, voff) do { const char* gb_ = (const char*)(gbase); asm volatile("" : "+s"(gb_)); _Pragma("unroll") for (int _i = 0; _i < 2; ++_i) { unsigned vo_ = (voff)[_i]; asm volatile("" : "+v"(vo_));        \
;         __builtin_amdgcn_global_load_lds((const unsigned*)(gb_ + vo_), (PG8_LAS unsigned*)(lds + (bufoff) + ldsw + _i * 8192), 16, 0, 0); } } while (0)
; #define PG8_LDA(dst, b, h) do { _Pragma("unroll") for (int m = 0; m < 4; ++m) _Pragma("unroll") for (int k = 0; k < 2; ++k) dst[m][k] = *(const PG8_LAS bf16x8*)(lds + PG8_SA(b, h) + aoff + m * 2048 + k * 1024); } while (0)
; #define PG8_LDB(dst, b, h) do { _Pragma("unroll") for (int n = 0; n < 2; ++n) _Pragma("unroll") for (int k = 0; k < 2; ++k) dst[n][k] = *(const PG8_LAS bf16x8*)(lds + PG8_SB(b, h) + boff + n * 2048 + k * 1024); } while (0)
; #define PG8_MMA(ai, bj, At, Bt) do { __builtin_amdgcn_s_setprio(1); _Pragma("unroll") for (int m = 0; m < 4; ++m) _Pragma("unroll") for (int n = 0; n < 2; ++n) _Pragma("unroll") for (int k = 0; k < 2; ++k) \
;         acc[ai][bj][m][n] = __builtin_amdgcn_mfma_f32_16x16x32_bf16(Bt[n][k], At[m][k], acc[ai][bj][m][n], 0, 0, 0); __builtin_amdgcn_s_setprio(0); } while (0)
; #define PG8_WAIT_V(n) asm volatile("s_waitcnt vmcnt(" #n ")" ::: "memory")
; #define PG8_WAIT_L(n) asm volatile("s_waitcnt lgkmcnt(" #n ")" ::: "memory")
; #define PG8_BAR __builtin_amdgcn_s_barrier()
; #define PG8_SCHED __builtin_amdgcn_sched_barrier(0)
; template <class Epi, class Sched, bool ALIGN_EPI = false, bool SP2 = false>
; __device__ __forceinline__ void gemm_phase(PG8_LAS unsigned char* lds, const Gemm g, const Sched& S, const Epi& E) {
;     ...
;             PG8_WAIT_V(8); PG8_WAIT_L(0); PG8_BAR; PG8_MMA(0, 0, At, B0); PG8_MMA(0, 1, At, B1); PG8_BAR; PG8_SCHED;
;             PG8_LDA(At, 0, 1); PG8_STAGE(PG8_SB(0, 0), b2, voffB); PG8_STAGE(PG8_SB(0, 1), b2 + hstep, voffB); PG8_STAGE(PG8_SA(0, 0), a2, voffA);
;             PG8_WAIT_V(8); PG8_WAIT_L(0); PG8_BAR; PG8_MMA(1, 0, At, B0); PG8_MMA(1, 1, At, B1); PG8_BAR; PG8_SCHED;
;             PG8_LDB(B0, 1, 0); PG8_LDB(B1, 1, 1); PG8_SCHED; PG8_LDA(At, 1, 0); PG8_STAGE(PG8_SA(0, 1), a2 + hstep, voffA);
;             PG8_WAIT_V(8); PG8_WAIT_L(0); PG8_BAR; PG8_MMA(0, 0, At, B0); PG8_MMA(0, 1, At, B1); PG8_BAR; PG8_SCHED;
	s_setprio 1
	s_waitcnt lgkmcnt(0)
	v_mfma_f32_16x16x32_bf16 v[62:65], v[82:85], v[178:181], v[62:65]
	v_mfma_f32_16x16x32_bf16 v[62:65], v[86:89], v[190:193], v[62:65]
	v_mfma_f32_16x16x32_bf16 v[58:61], v[94:97], v[190:193], v[58:61]
	v_mfma_f32_16x16x32_bf16 v[58:61], v[90:93], v[178:181], v[58:61]
	v_mfma_f32_16x16x32_bf16 v[42:45], v[90:93], v[194:197], v[42:45]
	v_mfma_f32_16x16x32_bf16 v[42:45], v[94:97], v[198:201], v[42:45]
	v_mfma_f32_16x16x32_bf16 v[46:49], v[86:89], v[198:201], v[46:49]
	v_mfma_f32_16x16x32_bf16 v[46:49], v[82:85], v[194:197], v[46:49]
	v_mfma_f32_16x16x32_bf16 v[30:33], v[82:85], v[202:205], v[30:33]
	v_mfma_f32_16x16x32_bf16 v[30:33], v[86:89], v[206:209], v[30:33]
	v_mfma_f32_16x16x32_bf16 v[26:29], v[94:97], v[206:209], v[26:29]
	v_mfma_f32_16x16x32_bf16 v[26:29], v[90:93], v[202:205], v[26:29]
	v_mfma_f32_16x16x32_bf16 v[10:13], v[90:93], v[210:213], v[10:13]
	v_mfma_f32_16x16x32_bf16 v[10:13], v[94:97], v[220:223], v[10:13]
	v_mfma_f32_16x16x32_bf16 v[14:17], v[86:89], v[220:223], v[14:17]
	v_mfma_f32_16x16x32_bf16 v[14:17], v[82:85], v[210:213], v[14:17]
	s_setprio 0
	s_setprio 1
	v_mfma_f32_16x16x32_bf16 v[54:57], v[146:149], v[178:181], v[54:57]
	v_mfma_f32_16x16x32_bf16 v[54:57], v[150:153], v[190:193], v[54:57]
	v_mfma_f32_16x16x32_bf16 v[50:53], v[158:161], v[190:193], v[50:53]
	v_mfma_f32_16x16x32_bf16 v[50:53], v[154:157], v[178:181], v[50:53]
	v_mfma_f32_16x16x32_bf16 v[34:37], v[154:157], v[194:197], v[34:37]
	v_mfma_f32_16x16x32_bf16 v[34:37], v[158:161], v[198:201], v[34:37]
	v_mfma_f32_16x16x32_bf16 v[38:41], v[150:153], v[198:201], v[38:41]
	v_mfma_f32_16x16x32_bf16 v[38:41], v[146:149], v[194:197], v[38:41]
	v_mfma_f32_16x16x32_bf16 v[22:25], v[146:149], v[202:205], v[22:25]
	v_mfma_f32_16x16x32_bf16 v[22:25], v[150:153], v[206:209], v[22:25]
	v_mfma_f32_16x16x32_bf16 v[18:21], v[158:161], v[206:209], v[18:21]
	v_mfma_f32_16x16x32_bf16 v[18:21], v[154:157], v[202:205], v[18:21]
	v_mfma_f32_16x16x32_bf16 v[2:5], v[154:157], v[210:213], v[2:5]
	v_mfma_f32_16x16x32_bf16 v[2:5], v[158:161], v[220:223], v[2:5]
	v_mfma_f32_16x16x32_bf16 v[6:9], v[150:153], v[220:223], v[6:9]
	v_mfma_f32_16x16x32_bf16 v[6:9], v[146:149], v[210:213], v[6:9]
	s_setprio 0
	s_barrier
	s_add_i32 s54, 0, 0x18000
	s_add_i32 s55, 0, 0x1c000
	ds_read_b128 v[82:85], v244 offset:32768
	ds_read_b128 v[86:89], v244 offset:33792
	ds_read_b128 v[90:93], v244 offset:34816
	ds_read_b128 v[94:97], v244 offset:35840
	ds_read_b128 v[146:149], v244 offset:49152
	ds_read_b128 v[150:153], v244 offset:50176
	ds_read_b128 v[154:157], v244 offset:51200
	ds_read_b128 v[158:161], v244 offset:52224
	s_add_u32 s14, s22, 0x80000
	s_addc_u32 s15, s23, 0
	s_mov_b32 m0, s29
	ds_read_b128 v[178:181], v188 offset:32768
	ds_read_b128 v[190:193], v188 offset:33792
	ds_read_b128 v[194:197], v188 offset:34816
	ds_read_b128 v[198:201], v188 offset:35840
	ds_read_b128 v[202:205], v188 offset:36864
	ds_read_b128 v[206:209], v188 offset:37888
	ds_read_b128 v[210:213], v188 offset:38912
	ds_read_b128 v[220:223], v188 offset:39936
	s_nop 0
	global_load_lds_dwordx4 v1, s[14:15]
	s_mov_b32 m0, s33
	s_nop 0
	global_load_lds_dwordx4 v164, s[14:15]
	s_waitcnt vmcnt(8)
	s_waitcnt lgkmcnt(0)
	s_barrier
	s_setprio 1
	s_waitcnt lgkmcnt(0)
	v_mfma_f32_16x16x32_bf16 v[142:145], v[82:85], v[178:181], v[142:145]
	v_mfma_f32_16x16x32_bf16 v[142:145], v[86:89], v[190:193], v[142:145]
	v_mfma_f32_16x16x32_bf16 v[138:141], v[94:97], v[190:193], v[138:141]
	v_mfma_f32_16x16x32_bf16 v[138:141], v[90:93], v[178:181], v[138:141]
	v_mfma_f32_16x16x32_bf16 v[122:125], v[90:93], v[194:197], v[122:125]
	v_mfma_f32_16x16x32_bf16 v[122:125], v[94:97], v[198:201], v[122:125]
	v_mfma_f32_16x16x32_bf16 v[126:129], v[86:89], v[198:201], v[126:129]
	v_mfma_f32_16x16x32_bf16 v[126:129], v[82:85], v[194:197], v[126:129]
	v_mfma_f32_16x16x32_bf16 v[110:113], v[82:85], v[202:205], v[110:113]
	v_mfma_f32_16x16x32_bf16 v[110:113], v[86:89], v[206:209], v[110:113]
	v_mfma_f32_16x16x32_bf16 v[106:109], v[94:97], v[206:209], v[106:109]
	v_mfma_f32_16x16x32_bf16 v[106:109], v[90:93], v[202:205], v[106:109]
	v_mfma_f32_16x16x32_bf16 v[74:77], v[90:93], v[210:213], v[74:77]
	v_mfma_f32_16x16x32_bf16 v[74:77], v[94:97], v[220:223], v[74:77]
	v_mfma_f32_16x16x32_bf16 v[78:81], v[86:89], v[220:223], v[78:81]
	v_mfma_f32_16x16x32_bf16 v[78:81], v[82:85], v[210:213], v[78:81]
	s_setprio 0
	s_setprio 1
	v_mfma_f32_16x16x32_bf16 v[134:137], v[146:149], v[178:181], v[134:137]
	v_mfma_f32_16x16x32_bf16 v[134:137], v[150:153], v[190:193], v[134:137]
	v_mfma_f32_16x16x32_bf16 v[130:133], v[158:161], v[190:193], v[130:133]
	v_mfma_f32_16x16x32_bf16 v[130:133], v[154:157], v[178:181], v[130:133]
	v_mfma_f32_16x16x32_bf16 v[114:117], v[154:157], v[194:197], v[114:117]
	v_mfma_f32_16x16x32_bf16 v[114:117], v[158:161], v[198:201], v[114:117]
	v_mfma_f32_16x16x32_bf16 v[118:121], v[150:153], v[198:201], v[118:121]
	v_mfma_f32_16x16x32_bf16 v[118:121], v[146:149], v[194:197], v[118:121]
	v_mfma_f32_16x16x32_bf16 v[102:105], v[146:149], v[202:205], v[102:105]
	v_mfma_f32_16x16x32_bf16 v[102:105], v[150:153], v[206:209], v[102:105]
	v_mfma_f32_16x16x32_bf16 v[98:101], v[158:161], v[206:209], v[98:101]
	v_mfma_f32_16x16x32_bf16 v[98:101], v[154:157], v[202:205], v[98:101]
	v_mfma_f32_16x16x32_bf16 v[66:69], v[154:157], v[210:213], v[66:69]
	v_mfma_f32_16x16x32_bf16 v[66:69], v[158:161], v[220:223], v[66:69]
	v_mfma_f32_16x16x32_bf16 v[70:73], v[150:153], v[220:223], v[70:73]
	v_mfma_f32_16x16x32_bf16 v[70:73], v[146:149], v[210:213], v[70:73]
	s_setprio 0
	s_barrier
; #define PG8_STAGE(bufoff, gbase, voff) do { const char* gb_ = (const char*)(gbase); asm volatile("" : "+s"(gb_)); _Pragma("unroll") for (int _i = 0; _i < 2; ++_i) { unsigned vo_ = (voff)[_i]; asm volatile("" : "+v"(vo_));        \
;         __builtin_amdgcn_global_load_lds((const unsigned*)(gb_ + vo_), (PG8_LAS unsigned*)(lds + (bufoff) + ldsw + _i * 8192), 16, 0, 0); } } while (0)
; #define PG8_LDA(dst, b, h) do { _Pragma("unroll") for (int m = 0; m < 4; ++m) _Pragma("unroll") for (int k = 0; k < 2; ++k) dst[m][k] = *(const PG8_LAS bf16x8*)(lds + PG8_SA(b, h) + aoff + m * 2048 + k * 1024); } while (0)
; #define PG8_LDB(dst, b, h) do { _Pragma("unroll") for (int n = 0; n < 2; ++n) _Pragma("unroll") for (int k = 0; k < 2; ++k) dst[n][k] = *(const PG8_LAS bf16x8*)(lds + PG8_SB(b, h) + boff + n * 2048 + k * 1024); } while (0)
; #define PG8_MMA(ai, bj, At, Bt) do { __builtin_amdgcn_s_setprio(1); _Pragma("unroll") for (int m = 0; m < 4; ++m) _Pragma("unroll") for (int n = 0; n < 2; ++n) _Pragma("unroll") for (int k = 0; k < 2; ++k) \
;         acc[ai][bj][m][n] = __builtin_amdgcn_mfma_f32_16x16x32_bf16(Bt[n][k], At[m][k], acc[ai][bj][m][n], 0, 0, 0); __builtin_amdgcn_s_setprio(0); } while (0)
; #define PG8_WAIT_V(n) asm volatile("s_waitcnt vmcnt(" #n ")" ::: "memory")
; #define PG8_WAIT_L(n) asm volatile("s_waitcnt lgkmcnt(" #n ")" ::: "memory")
; #define PG8_BAR __builtin_amdgcn_s_barrier()
; #define PG8_SCHED __builtin_amdgcn_sched_barrier(0)
; template <class Epi, class Sched, bool ALIGN_EPI = false, bool SP2 = false>
; __device__ __forceinline__ void gemm_phase(PG8_LAS unsigned char* lds, const Gemm g, const Sched& S, const Epi& E) {
;     ...
;             PG8_LDB(B0, 1, 0); PG8_LDB(B1, 1, 1); PG8_SCHED; PG8_LDA(At, 1, 0); PG8_STAGE(PG8_SA(0, 1), a2 + hstep, voffA);
;             PG8_WAIT_V(8); PG8_WAIT_L(0); PG8_BAR; PG8_MMA(0, 0, At, B0); PG8_MMA(0, 1, At, B1); PG8_BAR; PG8_SCHED;
;             PG8_LDA(At, 1, 1); PG8_STAGE(PG8_SB(1, 0), b3, voffB); PG8_STAGE(PG8_SB(1, 1), b3 + hstep, voffB); PG8_STAGE(PG8_SA(1, 0), a3, voffA);
;             PG8_WAIT_V(8); PG8_WAIT_L(0); PG8_BAR; PG8_MMA(1, 0, At, B0); PG8_MMA(1, 1, At, B1); PG8_BAR; PG8_SCHED;
;     ...
;         if constexpr (ALIGN_EPI) { if (wr == 0) PG8_BAR; }
	s_add_u32 s14, s20, 0x80
	s_addc_u32 s15, s21, 0
	s_add_i32 s22, s54, s26
	ds_read_b128 v[178:181], v188 offset:49152
	ds_read_b128 v[190:193], v188 offset:50176
	ds_read_b128 v[194:197], v188 offset:51200
	ds_read_b128 v[198:201], v188 offset:52224
	ds_read_b128 v[202:205], v188 offset:53248
	ds_read_b128 v[206:209], v188 offset:54272
	ds_read_b128 v[210:213], v188 offset:55296
	ds_read_b128 v[220:223], v188 offset:56320
	s_mov_b32 m0, s22
	s_nop 0
	global_load_lds_dwordx4 v162, s[14:15]
	s_add_i32 m0, s22, 0x2000
	s_nop 0
	global_load_lds_dwordx4 v184, s[14:15]
	s_add_u32 s14, s20, 0x80080
	s_addc_u32 s15, s21, 0
	s_add_i32 s20, s55, s26
	s_mov_b32 m0, s20
	s_nop 0
	global_load_lds_dwordx4 v162, s[14:15]
	s_add_i32 m0, s20, 0x2000
	s_nop 0
	global_load_lds_dwordx4 v184, s[14:15]
	s_mov_b32 m0, s38
	s_nop 0
	global_load_lds_dwordx4 v1, s[18:19]
	s_mov_b32 m0, s39
	s_nop 0
	global_load_lds_dwordx4 v164, s[18:19]
	s_waitcnt vmcnt(8)
	s_waitcnt lgkmcnt(0)
	s_barrier
	s_setprio 1
	s_waitcnt lgkmcnt(0)
	v_mfma_f32_16x16x32_bf16 v[62:65], v[82:85], v[178:181], v[62:65]
	v_mfma_f32_16x16x32_bf16 v[62:65], v[86:89], v[190:193], v[62:65]
	v_mfma_f32_16x16x32_bf16 v[58:61], v[94:97], v[190:193], v[58:61]
	v_mfma_f32_16x16x32_bf16 v[58:61], v[90:93], v[178:181], v[58:61]
	v_mfma_f32_16x16x32_bf16 v[42:45], v[90:93], v[194:197], v[42:45]
	v_mfma_f32_16x16x32_bf16 v[42:45], v[94:97], v[198:201], v[42:45]
	v_mfma_f32_16x16x32_bf16 v[46:49], v[86:89], v[198:201], v[46:49]
	v_mfma_f32_16x16x32_bf16 v[46:49], v[82:85], v[194:197], v[46:49]
	v_mfma_f32_16x16x32_bf16 v[30:33], v[82:85], v[202:205], v[30:33]
	v_mfma_f32_16x16x32_bf16 v[30:33], v[86:89], v[206:209], v[30:33]
	v_mfma_f32_16x16x32_bf16 v[26:29], v[94:97], v[206:209], v[26:29]
	v_mfma_f32_16x16x32_bf16 v[26:29], v[90:93], v[202:205], v[26:29]
	v_mfma_f32_16x16x32_bf16 v[10:13], v[90:93], v[210:213], v[10:13]
	v_mfma_f32_16x16x32_bf16 v[10:13], v[94:97], v[220:223], v[10:13]
	v_mfma_f32_16x16x32_bf16 v[14:17], v[86:89], v[220:223], v[14:17]
	v_mfma_f32_16x16x32_bf16 v[14:17], v[82:85], v[210:213], v[14:17]
	s_setprio 0
	s_setprio 1
	v_mfma_f32_16x16x32_bf16 v[54:57], v[146:149], v[178:181], v[54:57]
	v_mfma_f32_16x16x32_bf16 v[54:57], v[150:153], v[190:193], v[54:57]
	v_mfma_f32_16x16x32_bf16 v[50:53], v[158:161], v[190:193], v[50:53]
	v_mfma_f32_16x16x32_bf16 v[50:53], v[154:157], v[178:181], v[50:53]
	v_mfma_f32_16x16x32_bf16 v[34:37], v[154:157], v[194:197], v[34:37]
	v_mfma_f32_16x16x32_bf16 v[34:37], v[158:161], v[198:201], v[34:37]
	v_mfma_f32_16x16x32_bf16 v[38:41], v[150:153], v[198:201], v[38:41]
	v_mfma_f32_16x16x32_bf16 v[38:41], v[146:149], v[194:197], v[38:41]
	v_mfma_f32_16x16x32_bf16 v[22:25], v[146:149], v[202:205], v[22:25]
	v_mfma_f32_16x16x32_bf16 v[22:25], v[150:153], v[206:209], v[22:25]
	v_mfma_f32_16x16x32_bf16 v[18:21], v[158:161], v[206:209], v[18:21]
	v_mfma_f32_16x16x32_bf16 v[18:21], v[154:157], v[202:205], v[18:21]
	v_mfma_f32_16x16x32_bf16 v[2:5], v[154:157], v[210:213], v[2:5]
	v_mfma_f32_16x16x32_bf16 v[2:5], v[158:161], v[220:223], v[2:5]
	v_mfma_f32_16x16x32_bf16 v[6:9], v[150:153], v[220:223], v[6:9]
	v_mfma_f32_16x16x32_bf16 v[6:9], v[146:149], v[210:213], v[6:9]
	s_setprio 0
	s_barrier
	s_add_i32 s53, s53, 2
	s_add_u32 s51, s51, 0x100
	s_addc_u32 s52, s52, 0
	s_cmp_gt_u32 s53, 29
	s_mov_b64 s[14:15], s[16:17]
	s_cbranch_scc0 .LBB0_634
	s_and_b64 vcc, exec, s[2:3]
	s_cbranch_vccz .LBB0_637
	s_barrier

; #define PG8_STAGE(bufoff, gbase, voff) do { const char* gb_ = (const char*)(gbase); asm volatile("" : "+s"(gb_)); _Pragma("unroll") for (int _i = 0; _i < 2; ++_i) { unsigned vo_ = (voff)[_i]; asm volatile("" : "+v"(vo_));        \
;         __builtin_amdgcn_global_load_lds((const unsigned*)(gb_ + vo_), (PG8_LAS unsigned*)(lds + (bufoff) + ldsw + _i * 8192), 16, 0, 0); } } while (0)
; #define PG8_LDA(dst, b, h) do { _Pragma("unroll") for (int m = 0; m < 4; ++m) _Pragma("unroll") for (int k = 0; k < 2; ++k) dst[m][k] = *(const PG8_LAS bf16x8*)(lds + PG8_SA(b, h) + aoff + m * 2048 + k * 1024); } while (0)
; #define PG8_WAIT_V(n) asm volatile("s_waitcnt vmcnt(" #n ")" ::: "memory")
; #define PG8_WAIT_L(n) asm volatile("s_waitcnt lgkmcnt(" #n ")" ::: "memory")
; template <class Epi, class Sched, bool ALIGN_EPI = false, bool SP2 = false>
; __device__ __forceinline__ void gemm_phase(PG8_LAS unsigned char* lds, const Gemm g, const Sched& S, const Epi& E) {
;     ...
;             const bool last = (t == nt - 2);
;             const char* a1 = cA + (size_t)(t + 1) * kstep;
;             const char* a2 = last ? nA : cA + (size_t)(t + 2) * kstep; const char* b2 = last ? nB : cB + (size_t)(t + 2) * kstep;
;             const char* a3 = a2 + kstep; const char* b3 = b2 + kstep;
;             if (last && has_next) S.a_ready(nxt);
;             if constexpr (SP2) {
;             PG8_LDB(B0, 0, 0); PG8_LDB(B1, 0, 1); PG8_SCHED; PG8_LDA(At, 0, 0); PG8_STAGE(PG8_SA(1, 1), a1 + hstep, voffA);
;             PG8_WAIT_V(8); PG8_WAIT_L(0); PG8_BAR; PG8_MMA(0, 0, At, B0); PG8_MMA(0, 1, At, B1); PG8_BAR; PG8_SCHED;
;             PG8_LDA(At, 0, 1); PG8_STAGE(PG8_SB(0, 0), b2, voffB); PG8_STAGE(PG8_SB(0, 1), b2 + hstep, voffB); PG8_STAGE(PG8_SA(0, 0), a2, voffA);
;             PG8_WAIT_V(8); PG8_WAIT_L(0); PG8_BAR; PG8_MMA(1, 0, At, B0); PG8_MMA(1, 1, At, B1); PG8_BAR; PG8_SCHED;
;             PG8_LDB(B0, 1, 0); PG8_LDB(B1, 1, 1); PG8_SCHED; PG8_LDA(At, 1, 0); PG8_STAGE(PG8_SA(0, 1), a2 + hstep, voffA);
;             PG8_WAIT_V(8); PG8_WAIT_L(0); PG8_BAR; PG8_MMA(0, 0, At, B0); PG8_MMA(0, 1, At, B1); PG8_BAR; PG8_SCHED;
;             PG8_LDA(At, 1, 1); PG8_STAGE(PG8_SB(1, 0), b3, voffB); PG8_STAGE(PG8_SB(1, 1), b3 + hstep, voffB); PG8_STAGE(PG8_SA(1, 0), a3, voffA);
;             PG8_WAIT_V(8); PG8_WAIT_L(0); PG8_BAR; PG8_MMA(1, 0, At, B0); PG8_MMA(1, 1, At, B1); PG8_BAR; PG8_SCHED;
.LBB0_707:
	s_add_u32 s2, s4, 0x100
	s_addc_u32 s3, s5, 0
	s_cmpk_eq_i32 s35, 0x54
	s_cselect_b32 s10, s52, s2
	s_cselect_b32 s11, s53, s3
	s_cselect_b32 s8, s42, s31
	s_cselect_b32 s9, s43, s34
	s_add_u32 s6, s10, 0x80
	s_addc_u32 s7, s11, 0
	s_add_i32 s38, 0, 0x10000
	s_add_i32 s39, 0, 0x14000
	ds_read_b128 v[34:37], v244
	ds_read_b128 v[38:41], v244 offset:1024
	ds_read_b128 v[98:101], v244 offset:2048
	ds_read_b128 v[102:105], v244 offset:3072
	ds_read_b128 v[146:149], v244 offset:16384
	ds_read_b128 v[150:153], v244 offset:17408
	ds_read_b128 v[154:157], v244 offset:18432
	ds_read_b128 v[158:161], v244 offset:19456
	s_add_u32 s4, s4, 0x160080
	s_addc_u32 s5, s5, 0
	ds_read_b128 v[178:181], v194
	ds_read_b128 v[182:185], v194 offset:1024
	ds_read_b128 v[186:189], v194 offset:2048
	ds_read_b128 v[196:199], v194 offset:3072
	ds_read_b128 v[200:203], v194 offset:4096
	ds_read_b128 v[204:207], v194 offset:5120
	ds_read_b128 v[208:211], v194 offset:6144
	ds_read_b128 v[212:215], v194 offset:7168
	s_add_i32 m0, s16, 0xc000
	s_nop 0
	global_load_lds_dwordx4 v1, s[4:5]
	s_add_i32 m0, s16, 0xe000
	s_nop 0
	global_load_lds_dwordx4 v164, s[4:5]
	s_waitcnt vmcnt(8)
	s_waitcnt lgkmcnt(0)
	s_barrier
	s_setprio 1
	s_waitcnt lgkmcnt(0)
	v_mfma_f32_16x16x32_bf16 v[142:145], v[34:37], v[178:181], v[142:145]
	v_mfma_f32_16x16x32_bf16 v[142:145], v[38:41], v[182:185], v[142:145]
	v_mfma_f32_16x16x32_bf16 v[138:141], v[102:105], v[182:185], v[138:141]
	v_mfma_f32_16x16x32_bf16 v[138:141], v[98:101], v[178:181], v[138:141]
	v_mfma_f32_16x16x32_bf16 v[130:133], v[98:101], v[186:189], v[130:133]
	v_mfma_f32_16x16x32_bf16 v[130:133], v[102:105], v[196:199], v[130:133]
	v_mfma_f32_16x16x32_bf16 v[134:137], v[38:41], v[196:199], v[134:137]
	v_mfma_f32_16x16x32_bf16 v[134:137], v[34:37], v[186:189], v[134:137]
	v_mfma_f32_16x16x32_bf16 v[126:129], v[34:37], v[200:203], v[126:129]
	v_mfma_f32_16x16x32_bf16 v[126:129], v[38:41], v[204:207], v[126:129]
	v_mfma_f32_16x16x32_bf16 v[122:125], v[102:105], v[204:207], v[122:125]
	v_mfma_f32_16x16x32_bf16 v[122:125], v[98:101], v[200:203], v[122:125]
	v_mfma_f32_16x16x32_bf16 v[114:117], v[98:101], v[208:211], v[114:117]
	v_mfma_f32_16x16x32_bf16 v[114:117], v[102:105], v[212:215], v[114:117]
	v_mfma_f32_16x16x32_bf16 v[118:121], v[38:41], v[212:215], v[118:121]
	v_mfma_f32_16x16x32_bf16 v[118:121], v[34:37], v[208:211], v[118:121]
	s_setprio 0
	s_setprio 1
	v_mfma_f32_16x16x32_bf16 v[70:73], v[146:149], v[178:181], v[70:73]
	v_mfma_f32_16x16x32_bf16 v[70:73], v[150:153], v[182:185], v[70:73]
	v_mfma_f32_16x16x32_bf16 v[66:69], v[158:161], v[182:185], v[66:69]
	v_mfma_f32_16x16x32_bf16 v[66:69], v[154:157], v[178:181], v[66:69]
	v_mfma_f32_16x16x32_bf16 v[58:61], v[154:157], v[186:189], v[58:61]
	v_mfma_f32_16x16x32_bf16 v[58:61], v[158:161], v[196:199], v[58:61]
	v_mfma_f32_16x16x32_bf16 v[62:65], v[150:153], v[196:199], v[62:65]
	v_mfma_f32_16x16x32_bf16 v[62:65], v[146:149], v[186:189], v[62:65]
	v_mfma_f32_16x16x32_bf16 v[54:57], v[146:149], v[200:203], v[54:57]
	v_mfma_f32_16x16x32_bf16 v[54:57], v[150:153], v[204:207], v[54:57]
	v_mfma_f32_16x16x32_bf16 v[50:53], v[158:161], v[204:207], v[50:53]
	v_mfma_f32_16x16x32_bf16 v[50:53], v[154:157], v[200:203], v[50:53]
	v_mfma_f32_16x16x32_bf16 v[42:45], v[154:157], v[208:211], v[42:45]
	v_mfma_f32_16x16x32_bf16 v[42:45], v[158:161], v[212:215], v[42:45]
	v_mfma_f32_16x16x32_bf16 v[46:49], v[150:153], v[212:215], v[46:49]
	v_mfma_f32_16x16x32_bf16 v[46:49], v[146:149], v[208:211], v[46:49]
	s_setprio 0
	s_barrier
	s_mov_b64 s[4:5], s[8:9]
	s_add_i32 s38, s38, s15
	ds_read_b128 v[178:181], v194 offset:16384
	ds_read_b128 v[182:185], v194 offset:17408
	ds_read_b128 v[186:189], v194 offset:18432
	ds_read_b128 v[196:199], v194 offset:19456
	ds_read_b128 v[200:203], v194 offset:20480
	ds_read_b128 v[204:207], v194 offset:21504
	ds_read_b128 v[208:211], v194 offset:22528
	ds_read_b128 v[212:215], v194 offset:23552
	s_mov_b32 m0, s38
	s_nop 0
	global_load_lds_dwordx4 v162, s[4:5]
	s_add_i32 m0, s38, 0x2000
	s_nop 0
	global_load_lds_dwordx4 v190, s[4:5]
	s_add_u32 s4, s8, 0x160000
	s_addc_u32 s5, s9, 0
	s_add_i32 s38, s39, s15
	s_mov_b32 m0, s38
	s_nop 0
	global_load_lds_dwordx4 v162, s[4:5]
	s_add_i32 m0, s38, 0x2000
	s_nop 0
	global_load_lds_dwordx4 v190, s[4:5]
	s_mov_b64 s[4:5], s[10:11]
	s_mov_b32 m0, s16
	s_nop 0
	global_load_lds_dwordx4 v1, s[4:5]
	s_mov_b32 m0, s17
	s_nop 0
	global_load_lds_dwordx4 v164, s[4:5]
	s_waitcnt vmcnt(8)
	s_waitcnt lgkmcnt(0)
	s_barrier
; #define PG8_STAGE(bufoff, gbase, voff) do { const char* gb_ = (const char*)(gbase); asm volatile("" : "+s"(gb_)); _Pragma("unroll") for (int _i = 0; _i < 2; ++_i) { unsigned vo_ = (voff)[_i]; asm volatile("" : "+v"(vo_));        \
;         __builtin_amdgcn_global_load_lds((const unsigned*)(gb_ + vo_), (PG8_LAS unsigned*)(lds + (bufoff) + ldsw + _i * 8192), 16, 0, 0); } } while (0)
; #define PG8_LDA(dst, b, h) do { _Pragma("unroll") for (int m = 0; m < 4; ++m) _Pragma("unroll") for (int k = 0; k < 2; ++k) dst[m][k] = *(const PG8_LAS bf16x8*)(lds + PG8_SA(b, h) + aoff + m * 2048 + k * 1024); } while (0)
; #define PG8_LDB(dst, b, h) do { _Pragma("unroll") for (int n = 0; n < 2; ++n) _Pragma("unroll") for (int k = 0; k < 2; ++k) dst[n][k] = *(const PG8_LAS bf16x8*)(lds + PG8_SB(b, h) + boff + n * 2048 + k * 1024); } while (0)
; #define PG8_MMA(ai, bj, At, Bt) do { __builtin_amdgcn_s_setprio(1); _Pragma("unroll") for (int m = 0; m < 4; ++m) _Pragma("unroll") for (int n = 0; n < 2; ++n) _Pragma("unroll") for (int k = 0; k < 2; ++k) \
;         acc[ai][bj][m][n] = __builtin_amdgcn_mfma_f32_16x16x32_bf16(Bt[n][k], At[m][k], acc[ai][bj][m][n], 0, 0, 0); __builtin_amdgcn_s_setprio(0); } while (0)
; #define PG8_WAIT_V(n) asm volatile("s_waitcnt vmcnt(" #n ")" ::: "memory")
; #define PG8_WAIT_L(n) asm volatile("s_waitcnt lgkmcnt(" #n ")" ::: "memory")
; #define PG8_BAR __builtin_amdgcn_s_barrier()
; #define PG8_SCHED __builtin_amdgcn_sched_barrier(0)
; template <class Epi, class Sched, bool ALIGN_EPI = false, bool SP2 = false>
; __device__ __forceinline__ void gemm_phase(PG8_LAS unsigned char* lds, const Gemm g, const Sched& S, const Epi& E) {
;     ...
;             PG8_WAIT_V(8); PG8_WAIT_L(0); PG8_BAR; PG8_MMA(0, 0, At, B0); PG8_MMA(0, 1, At, B1); PG8_BAR; PG8_SCHED;
;             PG8_LDA(At, 0, 1); PG8_STAGE(PG8_SB(0, 0), b2, voffB); PG8_STAGE(PG8_SB(0, 1), b2 + hstep, voffB); PG8_STAGE(PG8_SA(0, 0), a2, voffA);
;             PG8_WAIT_V(8); PG8_WAIT_L(0); PG8_BAR; PG8_MMA(1, 0, At, B0); PG8_MMA(1, 1, At, B1); PG8_BAR; PG8_SCHED;
;             PG8_LDB(B0, 1, 0); PG8_LDB(B1, 1, 1); PG8_SCHED; PG8_LDA(At, 1, 0); PG8_STAGE(PG8_SA(0, 1), a2 + hstep, voffA);
;             PG8_WAIT_V(8); PG8_WAIT_L(0); PG8_BAR; PG8_MMA(0, 0, At, B0); PG8_MMA(0, 1, At, B1); PG8_BAR; PG8_SCHED;
	s_setprio 1
	s_waitcnt lgkmcnt(0)
	v_mfma_f32_16x16x32_bf16 v[110:113], v[34:37], v[178:181], v[110:113]
	v_mfma_f32_16x16x32_bf16 v[110:113], v[38:41], v[182:185], v[110:113]
	v_mfma_f32_16x16x32_bf16 v[106:109], v[98:101], v[178:181], v[106:109]
	v_mfma_f32_16x16x32_bf16 v[106:109], v[102:105], v[182:185], v[106:109]
	v_mfma_f32_16x16x32_bf16 v[94:97], v[34:37], v[186:189], v[94:97]
	v_mfma_f32_16x16x32_bf16 v[94:97], v[38:41], v[196:199], v[94:97]
	v_mfma_f32_16x16x32_bf16 v[90:93], v[98:101], v[186:189], v[90:93]
	v_mfma_f32_16x16x32_bf16 v[90:93], v[102:105], v[196:199], v[90:93]
	v_mfma_f32_16x16x32_bf16 v[86:89], v[34:37], v[200:203], v[86:89]
	v_mfma_f32_16x16x32_bf16 v[86:89], v[38:41], v[204:207], v[86:89]
	v_mfma_f32_16x16x32_bf16 v[82:85], v[98:101], v[200:203], v[82:85]
	v_mfma_f32_16x16x32_bf16 v[82:85], v[102:105], v[204:207], v[82:85]
	v_mfma_f32_16x16x32_bf16 v[34:37], v[34:37], v[208:211], v[78:81]
	v_mfma_f32_16x16x32_bf16 v[34:37], v[38:41], v[212:215], v[34:37]
	v_mfma_f32_16x16x32_bf16 v[38:41], v[98:101], v[208:211], v[74:77]
	v_mfma_f32_16x16x32_bf16 v[38:41], v[102:105], v[212:215], v[38:41]
	s_setprio 0
	s_setprio 1
	v_mfma_f32_16x16x32_bf16 v[30:33], v[146:149], v[178:181], v[30:33]
	v_mfma_f32_16x16x32_bf16 v[30:33], v[150:153], v[182:185], v[30:33]
	v_mfma_f32_16x16x32_bf16 v[26:29], v[158:161], v[182:185], v[26:29]
	v_mfma_f32_16x16x32_bf16 v[26:29], v[154:157], v[178:181], v[26:29]
	v_mfma_f32_16x16x32_bf16 v[18:21], v[154:157], v[186:189], v[18:21]
	v_mfma_f32_16x16x32_bf16 v[18:21], v[158:161], v[196:199], v[18:21]
	v_mfma_f32_16x16x32_bf16 v[22:25], v[150:153], v[196:199], v[22:25]
	v_mfma_f32_16x16x32_bf16 v[22:25], v[146:149], v[186:189], v[22:25]
	v_mfma_f32_16x16x32_bf16 v[14:17], v[146:149], v[200:203], v[14:17]
	v_mfma_f32_16x16x32_bf16 v[14:17], v[150:153], v[204:207], v[14:17]
	v_mfma_f32_16x16x32_bf16 v[10:13], v[158:161], v[204:207], v[10:13]
	v_mfma_f32_16x16x32_bf16 v[10:13], v[154:157], v[200:203], v[10:13]
	v_mfma_f32_16x16x32_bf16 v[2:5], v[154:157], v[208:211], v[2:5]
	v_mfma_f32_16x16x32_bf16 v[2:5], v[158:161], v[212:215], v[2:5]
	v_mfma_f32_16x16x32_bf16 v[6:9], v[150:153], v[212:215], v[6:9]
	v_mfma_f32_16x16x32_bf16 v[6:9], v[146:149], v[208:211], v[6:9]
	s_setprio 0
	s_barrier
	s_add_i32 s38, 0, 0x18000
	s_add_i32 s39, 0, 0x1c000
	ds_read_b128 v[74:77], v244 offset:32768
	ds_read_b128 v[78:81], v244 offset:33792
	ds_read_b128 v[98:101], v244 offset:34816
	ds_read_b128 v[102:105], v244 offset:35840
	ds_read_b128 v[146:149], v244 offset:49152
	ds_read_b128 v[150:153], v244 offset:50176
	ds_read_b128 v[154:157], v244 offset:51200
	ds_read_b128 v[158:161], v244 offset:52224
	s_add_u32 s4, s10, 0x160000
	s_addc_u32 s5, s11, 0
	s_mov_b32 m0, s18
	ds_read_b128 v[178:181], v194 offset:32768
	ds_read_b128 v[182:185], v194 offset:33792
	ds_read_b128 v[186:189], v194 offset:34816
	ds_read_b128 v[196:199], v194 offset:35840
	ds_read_b128 v[200:203], v194 offset:36864
	ds_read_b128 v[204:207], v194 offset:37888
	ds_read_b128 v[208:211], v194 offset:38912
	ds_read_b128 v[212:215], v194 offset:39936
	s_nop 0
	global_load_lds_dwordx4 v1, s[4:5]
	s_mov_b32 m0, s19
	s_nop 0
	global_load_lds_dwordx4 v164, s[4:5]
	s_waitcnt vmcnt(8)
	s_waitcnt lgkmcnt(0)
	s_barrier
	s_setprio 1
	s_waitcnt lgkmcnt(0)
	v_mfma_f32_16x16x32_bf16 v[142:145], v[74:77], v[178:181], v[142:145]
	v_mfma_f32_16x16x32_bf16 v[142:145], v[78:81], v[182:185], v[142:145]
	v_mfma_f32_16x16x32_bf16 v[138:141], v[102:105], v[182:185], v[138:141]
	v_mfma_f32_16x16x32_bf16 v[138:141], v[98:101], v[178:181], v[138:141]
	v_mfma_f32_16x16x32_bf16 v[130:133], v[98:101], v[186:189], v[130:133]
	v_mfma_f32_16x16x32_bf16 v[130:133], v[102:105], v[196:199], v[130:133]
	v_mfma_f32_16x16x32_bf16 v[134:137], v[78:81], v[196:199], v[134:137]
	v_mfma_f32_16x16x32_bf16 v[134:137], v[74:77], v[186:189], v[134:137]
	v_mfma_f32_16x16x32_bf16 v[126:129], v[74:77], v[200:203], v[126:129]
	v_mfma_f32_16x16x32_bf16 v[126:129], v[78:81], v[204:207], v[126:129]
	v_mfma_f32_16x16x32_bf16 v[122:125], v[102:105], v[204:207], v[122:125]
	v_mfma_f32_16x16x32_bf16 v[122:125], v[98:101], v[200:203], v[122:125]
	v_mfma_f32_16x16x32_bf16 v[114:117], v[98:101], v[208:211], v[114:117]
	v_mfma_f32_16x16x32_bf16 v[114:117], v[102:105], v[212:215], v[114:117]
	v_mfma_f32_16x16x32_bf16 v[118:121], v[78:81], v[212:215], v[118:121]
	v_mfma_f32_16x16x32_bf16 v[118:121], v[74:77], v[208:211], v[118:121]
	s_setprio 0
	s_setprio 1
	v_mfma_f32_16x16x32_bf16 v[70:73], v[146:149], v[178:181], v[70:73]
	v_mfma_f32_16x16x32_bf16 v[70:73], v[150:153], v[182:185], v[70:73]
	v_mfma_f32_16x16x32_bf16 v[66:69], v[158:161], v[182:185], v[66:69]
	v_mfma_f32_16x16x32_bf16 v[66:69], v[154:157], v[178:181], v[66:69]
	v_mfma_f32_16x16x32_bf16 v[58:61], v[154:157], v[186:189], v[58:61]
	v_mfma_f32_16x16x32_bf16 v[58:61], v[158:161], v[196:199], v[58:61]
	v_mfma_f32_16x16x32_bf16 v[62:65], v[150:153], v[196:199], v[62:65]
	v_mfma_f32_16x16x32_bf16 v[62:65], v[146:149], v[186:189], v[62:65]
	v_mfma_f32_16x16x32_bf16 v[54:57], v[146:149], v[200:203], v[54:57]
	v_mfma_f32_16x16x32_bf16 v[54:57], v[150:153], v[204:207], v[54:57]
	v_mfma_f32_16x16x32_bf16 v[50:53], v[158:161], v[204:207], v[50:53]
	v_mfma_f32_16x16x32_bf16 v[50:53], v[154:157], v[200:203], v[50:53]
	v_mfma_f32_16x16x32_bf16 v[42:45], v[154:157], v[208:211], v[42:45]
	v_mfma_f32_16x16x32_bf16 v[42:45], v[158:161], v[212:215], v[42:45]
	v_mfma_f32_16x16x32_bf16 v[46:49], v[150:153], v[212:215], v[46:49]
	v_mfma_f32_16x16x32_bf16 v[46:49], v[146:149], v[208:211], v[46:49]
	s_setprio 0
	s_barrier
; #define PG8_STAGE(bufoff, gbase, voff) do { const char* gb_ = (const char*)(gbase); asm volatile("" : "+s"(gb_)); _Pragma("unroll") for (int _i = 0; _i < 2; ++_i) { unsigned vo_ = (voff)[_i]; asm volatile("" : "+v"(vo_));        \
;         __builtin_amdgcn_global_load_lds((const unsigned*)(gb_ + vo_), (PG8_LAS unsigned*)(lds + (bufoff) + ldsw + _i * 8192), 16, 0, 0); } } while (0)
; #define PG8_LDA(dst, b, h) do { _Pragma("unroll") for (int m = 0; m < 4; ++m) _Pragma("unroll") for (int k = 0; k < 2; ++k) dst[m][k] = *(const PG8_LAS bf16x8*)(lds + PG8_SA(b, h) + aoff + m * 2048 + k * 1024); } while (0)
; #define PG8_WAIT_V(n) asm volatile("s_waitcnt vmcnt(" #n ")" ::: "memory")
; #define PG8_WAIT_L(n) asm volatile("s_waitcnt lgkmcnt(" #n ")" ::: "memory")
; #define PG8_BAR __builtin_amdgcn_s_barrier()
; #define PG8_SCHED __builtin_amdgcn_sched_barrier(0)
;     __device__ __forceinline__ void operator()(const f32x4 (&acc)[2][2][4][2], const Unit& u, int wr, int wc, int fr, int fq) const {
;         const int row0 = u.pm * BM + wr * 64 + fr, col0 = u.pn * BM + wc * 32 + 8 * fq, b = (u.pm * BM) / rows_per_batch;
;         const float* g = gate + (size_t)b * gate_bstride + col0;
;         float ssq[2][4];
; #pragma unroll
;         for (int ai = 0; ai < 2; ++ai)
; #pragma unroll
;             for (int m = 0; m < 4; ++m) ssq[ai][m] = 0.f;
;         f32x4 gv[2][2], Gv[2][2];
; #pragma unroll
;         for (int bj = 0; bj < 2; ++bj) { gv[bj][0] = *(const f32x4*)(g + bj * HALF); gv[bj][1] = *(const f32x4*)(g + bj * HALF + 4); Gv[bj][0] = (f32x4){0.f, 0.f, 0.f, 0.f}; Gv[bj][1] = (f32x4){0.f, 0.f, 0.f, 0.f};
;             if (Hn) { const float* sc = scnext + (size_t)b * gate_bstride + col0 + bj * HALF;
;                 Gv[bj][0] = *(const f32x4*)(gnext + col0 + bj * HALF) * (1.0f + *(const f32x4*)(sc)); Gv[bj][1] = *(const f32x4*)(gnext + col0 + bj * HALF + 4) * (1.0f + *(const f32x4*)(sc + 4)); } }
; template <class Epi, class Sched, bool ALIGN_EPI = false, bool SP2 = false>
; __device__ __forceinline__ void gemm_phase(PG8_LAS unsigned char* lds, const Gemm g, const Sched& S, const Epi& E) {
;     ...
;             PG8_LDA(At, 1, 1); PG8_STAGE(PG8_SB(1, 0), b3, voffB); PG8_STAGE(PG8_SB(1, 1), b3 + hstep, voffB); PG8_STAGE(PG8_SA(1, 0), a3, voffA);
;             PG8_WAIT_V(8); PG8_WAIT_L(0); PG8_BAR; PG8_MMA(1, 0, At, B0); PG8_MMA(1, 1, At, B1); PG8_BAR; PG8_SCHED;
	s_add_u32 s4, s8, 0x80
	s_addc_u32 s5, s9, 0
	s_add_i32 s10, s38, s15
	ds_read_b128 v[178:181], v194 offset:49152
	ds_read_b128 v[182:185], v194 offset:50176
	ds_read_b128 v[186:189], v194 offset:51200
	ds_read_b128 v[196:199], v194 offset:52224
	ds_read_b128 v[200:203], v194 offset:53248
	ds_read_b128 v[204:207], v194 offset:54272
	ds_read_b128 v[208:211], v194 offset:55296
	ds_read_b128 v[212:215], v194 offset:56320
	s_mov_b32 m0, s10
	s_nop 0
	global_load_lds_dwordx4 v162, s[4:5]
	s_add_i32 m0, s10, 0x2000
	s_nop 0
	global_load_lds_dwordx4 v190, s[4:5]
	s_add_u32 s4, s8, 0x160080
	s_addc_u32 s5, s9, 0
	s_add_i32 s8, s39, s15
	s_mov_b32 m0, s8
	s_nop 0
	global_load_lds_dwordx4 v162, s[4:5]
	s_add_i32 m0, s8, 0x2000
	s_nop 0
	global_load_lds_dwordx4 v190, s[4:5]
	s_mov_b32 m0, s24
	s_nop 0
	global_load_lds_dwordx4 v1, s[6:7]
	s_mov_b32 m0, s25
	s_nop 0
	global_load_lds_dwordx4 v164, s[6:7]
	s_waitcnt vmcnt(8)
	s_waitcnt lgkmcnt(0)
	s_barrier
	s_setprio 1
	s_waitcnt lgkmcnt(0)
	v_mfma_f32_16x16x32_bf16 v[110:113], v[74:77], v[178:181], v[110:113]
	v_mfma_f32_16x16x32_bf16 v[110:113], v[78:81], v[182:185], v[110:113]
	v_mfma_f32_16x16x32_bf16 v[94:97], v[74:77], v[186:189], v[94:97]
	v_mfma_f32_16x16x32_bf16 v[94:97], v[78:81], v[196:199], v[94:97]
	v_mfma_f32_16x16x32_bf16 v[86:89], v[74:77], v[200:203], v[86:89]
	v_mfma_f32_16x16x32_bf16 v[86:89], v[78:81], v[204:207], v[86:89]
	v_mfma_f32_16x16x32_bf16 v[34:37], v[74:77], v[208:211], v[34:37]
	v_mfma_f32_16x16x32_bf16 v[78:81], v[78:81], v[212:215], v[34:37]
	v_mfma_f32_16x16x32_bf16 v[106:109], v[98:101], v[178:181], v[106:109]
	v_mfma_f32_16x16x32_bf16 v[106:109], v[102:105], v[182:185], v[106:109]
	v_mfma_f32_16x16x32_bf16 v[90:93], v[98:101], v[186:189], v[90:93]
	v_mfma_f32_16x16x32_bf16 v[90:93], v[102:105], v[196:199], v[90:93]
	v_mfma_f32_16x16x32_bf16 v[82:85], v[98:101], v[200:203], v[82:85]
	v_mfma_f32_16x16x32_bf16 v[82:85], v[102:105], v[204:207], v[82:85]
	v_mfma_f32_16x16x32_bf16 v[34:37], v[98:101], v[208:211], v[38:41]
	v_mfma_f32_16x16x32_bf16 v[74:77], v[102:105], v[212:215], v[34:37]
	s_setprio 0
	s_setprio 1
	v_mfma_f32_16x16x32_bf16 v[30:33], v[146:149], v[178:181], v[30:33]
	v_mfma_f32_16x16x32_bf16 v[30:33], v[150:153], v[182:185], v[30:33]
	v_mfma_f32_16x16x32_bf16 v[26:29], v[158:161], v[182:185], v[26:29]
	v_mfma_f32_16x16x32_bf16 v[26:29], v[154:157], v[178:181], v[26:29]
	v_mfma_f32_16x16x32_bf16 v[18:21], v[154:157], v[186:189], v[18:21]
	v_mfma_f32_16x16x32_bf16 v[18:21], v[158:161], v[196:199], v[18:21]
	v_mfma_f32_16x16x32_bf16 v[22:25], v[150:153], v[196:199], v[22:25]
	v_mfma_f32_16x16x32_bf16 v[22:25], v[146:149], v[186:189], v[22:25]
	v_mfma_f32_16x16x32_bf16 v[14:17], v[146:149], v[200:203], v[14:17]
	v_mfma_f32_16x16x32_bf16 v[14:17], v[150:153], v[204:207], v[14:17]
	v_mfma_f32_16x16x32_bf16 v[10:13], v[158:161], v[204:207], v[10:13]
	v_mfma_f32_16x16x32_bf16 v[10:13], v[154:157], v[200:203], v[10:13]
	v_mfma_f32_16x16x32_bf16 v[2:5], v[154:157], v[208:211], v[2:5]
	v_mfma_f32_16x16x32_bf16 v[2:5], v[158:161], v[212:215], v[2:5]
	v_mfma_f32_16x16x32_bf16 v[6:9], v[150:153], v[212:215], v[6:9]
	v_mfma_f32_16x16x32_bf16 v[6:9], v[146:149], v[208:211], v[6:9]
	s_setprio 0
	s_barrier
	s_add_i32 s35, s35, 2
	s_add_u32 s31, s31, 0x100
	s_addc_u32 s34, s34, 0
	s_cmpk_gt_u32 s35, 0x55
	s_mov_b64 s[4:5], s[2:3]
	s_cbranch_scc0 .LBB0_707
	s_ashr_i32 s2, s29, 31
	s_lshr_b32 s2, s2, 27
	s_add_i32 s2, s29, s2
	s_ashr_i32 s2, s2, 5
	v_lshl_or_b32 v156, s30, 8, v193
	s_mul_i32 s5, s2, 0xc000
	v_ashrrev_i32_e32 v157, 31, v156
	s_mul_hi_i32 s4, s2, 0xc000
	s_add_u32 s2, s20, s5
	s_addc_u32 s3, s21, s4
	v_lshlrev_b64 v[34:35], 2, v[156:157]
	v_lshl_add_u64 v[38:39], s[2:3], 0, v[34:35]
	global_load_dwordx4 v[98:101], v[38:39], off offset:16
	global_load_dwordx4 v[102:105], v[38:39], off
	s_add_u32 s2, s22, s5
	s_addc_u32 s3, s23, s4
	v_lshl_add_u64 v[148:149], s[2:3], 0, v[34:35]
	v_lshl_add_u64 v[146:147], s[48:49], 0, v[34:35]
	v_mov_b32_e32 v158, 0
	v_cndmask_b32_e64 v34, 0, 1, s[46:47]
	v_cmp_ne_u32_e64 s[2:3], 1, v34
	s_andn2_b64 vcc, exec, s[46:47]
	v_mov_b32_e32 v159, v158
	v_mov_b32_e32 v160, v158
	v_mov_b32_e32 v161, v158
	v_mov_b32_e32 v178, v158
	v_mov_b32_e32 v179, v158
	v_mov_b32_e32 v180, v158
	v_mov_b32_e32 v181, v158
	s_cbranch_vccnz .LBB0_710
	global_load_dwordx4 v[34:37], v[148:149], off
	global_load_dwordx4 v[150:153], v[148:149], off offset:16
	global_load_dwordx4 v[158:161], v[146:147], off
	global_load_dwordx4 v[178:181], v[146:147], off offset:16
	s_waitcnt vmcnt(0)
	v_pk_add_f32 v[36:37], v[36:37], 1.0 op_sel_hi:[1,0]
	v_pk_add_f32 v[34:35], v[34:35], 1.0 op_sel_hi:[1,0]
	v_pk_add_f32 v[40:41], v[152:153], 1.0 op_sel_hi:[1,0]
	v_pk_add_f32 v[150:151], v[150:151], 1.0 op_sel_hi:[1,0]
	v_pk_mul_f32 v[160:161], v[160:161], v[36:37]
	v_pk_mul_f32 v[158:159], v[158:159], v[34:35]
	v_pk_mul_f32 v[180:181], v[180:181], v[40:41]
	v_pk_mul_f32 v[178:179], v[178:179], v[150:151]
